# GEMM K-loops: first iteration peeled with C=0 (no accumulator zeroing)
# speedup vs baseline: 1.0249x; 1.0012x over previous
.LBB0_228:
	s_ashr_i32 s39, s38, 31
	s_lshl_b64 s[40:41], s[38:39], 19
	v_readlane_b32 s42, v238, 7
	v_readlane_b32 s43, v238, 8
	s_add_u32 s40, s42, s40
	s_addc_u32 s41, s43, s41
	s_and_b64 s[42:43], s[2:3], exec
	s_cselect_b32 s5, s41, s1
	s_cselect_b32 s7, s40, s0
	s_ashr_i32 s37, s36, 31
	s_lshl_b64 s[42:43], s[36:37], 19
	s_add_u32 s42, s64, s42
	s_addc_u32 s43, s65, s43
	s_and_b64 s[44:45], s[2:3], exec
	s_cselect_b32 s33, s43, s9
	s_cselect_b32 s37, s42, s8
	s_add_u32 s0, s0, 0x40080
	s_addc_u32 s1, s1, 0
	s_add_u32 s39, s8, 0x100
	s_addc_u32 s46, s9, 0
	s_mov_b32 s47, -2
	ds_read_b128 v[144:147], v170
	ds_read_b128 v[148:151], v170 offset:1024
	ds_read_b128 v[152:155], v170 offset:2048
	ds_read_b128 v[156:159], v170 offset:3072
	ds_read_b128 v[162:165], v171
	ds_read_b128 v[174:177], v171 offset:1024
	ds_read_b128 v[178:181], v171 offset:2048
	ds_read_b128 v[182:185], v171 offset:3072
	s_add_u32 s8, s0, 0xfffc0080
	s_addc_u32 s9, s1, -1
	s_cmp_eq_u32 s47, 12
	s_cselect_b32 s45, s5, s9
	s_cselect_b32 s44, s7, s8
	s_cselect_b32 s9, s33, s46
	s_cselect_b32 s8, s37, s39
	v_lshl_add_u64 v[218:219], s[0:1], 0, v[136:137]
	s_add_i32 m0, s67, 0xc000
	ds_read_b128 v[186:189], v172
	ds_read_b128 v[190:193], v172 offset:1024
	ds_read_b128 v[194:197], v172 offset:2048
	ds_read_b128 v[198:201], v172 offset:3072
	ds_read_b128 v[202:205], v172 offset:4096
	ds_read_b128 v[206:209], v172 offset:5120
	ds_read_b128 v[210:213], v172 offset:6144
	ds_read_b128 v[214:217], v172 offset:7168
	global_load_lds_dwordx4 v[218:219], off
	v_lshl_add_u64 v[218:219], s[0:1], 0, v[138:139]
	s_add_i32 m0, s67, 0xe000
	s_nop 0
	global_load_lds_dwordx4 v[218:219], off
	s_waitcnt vmcnt(8)
	s_waitcnt lgkmcnt(0)
	s_barrier
	s_setprio 1
	s_waitcnt lgkmcnt(0)
	v_mfma_f32_16x16x32_bf16 v[124:127], v[144:147], v[186:189], 0
	v_mfma_f32_16x16x32_bf16 v[120:123], v[152:155], v[186:189], 0
	v_mfma_f32_16x16x32_bf16 v[108:111], v[144:147], v[194:197], 0
	v_mfma_f32_16x16x32_bf16 v[104:107], v[152:155], v[194:197], 0
	v_mfma_f32_16x16x32_bf16 v[92:95], v[144:147], v[202:205], 0
	v_mfma_f32_16x16x32_bf16 v[88:91], v[152:155], v[202:205], 0
	v_mfma_f32_16x16x32_bf16 v[76:79], v[144:147], v[210:213], 0
	v_mfma_f32_16x16x32_bf16 v[72:75], v[152:155], v[210:213], 0
	v_mfma_f32_16x16x32_bf16 v[124:127], v[148:151], v[190:193], v[124:127]
	v_mfma_f32_16x16x32_bf16 v[120:123], v[156:159], v[190:193], v[120:123]
	v_mfma_f32_16x16x32_bf16 v[108:111], v[148:151], v[198:201], v[108:111]
	v_mfma_f32_16x16x32_bf16 v[104:107], v[156:159], v[198:201], v[104:107]
	v_mfma_f32_16x16x32_bf16 v[92:95], v[148:151], v[206:209], v[92:95]
	v_mfma_f32_16x16x32_bf16 v[88:91], v[156:159], v[206:209], v[88:91]
	v_mfma_f32_16x16x32_bf16 v[76:79], v[148:151], v[214:217], v[76:79]
	v_mfma_f32_16x16x32_bf16 v[72:75], v[156:159], v[214:217], v[72:75]
	s_setprio 0
	s_setprio 1
	v_mfma_f32_16x16x32_bf16 v[116:119], v[162:165], v[186:189], 0
	v_mfma_f32_16x16x32_bf16 v[112:115], v[178:181], v[186:189], 0
	v_mfma_f32_16x16x32_bf16 v[100:103], v[162:165], v[194:197], 0
	v_mfma_f32_16x16x32_bf16 v[96:99], v[178:181], v[194:197], 0
	v_mfma_f32_16x16x32_bf16 v[84:87], v[162:165], v[202:205], 0
	v_mfma_f32_16x16x32_bf16 v[80:83], v[178:181], v[202:205], 0
	v_mfma_f32_16x16x32_bf16 v[68:71], v[162:165], v[210:213], 0
	v_mfma_f32_16x16x32_bf16 v[64:67], v[178:181], v[210:213], 0
	v_mfma_f32_16x16x32_bf16 v[116:119], v[174:177], v[190:193], v[116:119]
	v_mfma_f32_16x16x32_bf16 v[112:115], v[182:185], v[190:193], v[112:115]
	v_mfma_f32_16x16x32_bf16 v[100:103], v[174:177], v[198:201], v[100:103]
	v_mfma_f32_16x16x32_bf16 v[96:99], v[182:185], v[198:201], v[96:99]
	v_mfma_f32_16x16x32_bf16 v[84:87], v[174:177], v[206:209], v[84:87]
	v_mfma_f32_16x16x32_bf16 v[80:83], v[182:185], v[206:209], v[80:83]
	v_mfma_f32_16x16x32_bf16 v[68:71], v[174:177], v[214:217], v[68:71]
	v_mfma_f32_16x16x32_bf16 v[64:67], v[182:185], v[214:217], v[64:67]
	s_setprio 0
	s_barrier
	s_add_i32 s52, s79, s66
	v_lshl_add_u64 v[218:219], s[8:9], 0, v[130:131]
	s_mov_b32 m0, s52
	ds_read_b128 v[186:189], v172 offset:16384
	ds_read_b128 v[190:193], v172 offset:17408
	ds_read_b128 v[194:197], v172 offset:18432
	ds_read_b128 v[198:201], v172 offset:19456
	ds_read_b128 v[202:205], v172 offset:20480
	ds_read_b128 v[206:209], v172 offset:21504
	ds_read_b128 v[210:213], v172 offset:22528
	ds_read_b128 v[214:217], v172 offset:23552
	global_load_lds_dwordx4 v[218:219], off
	s_add_i32 m0, s52, 0x2000
	s_add_u32 s52, s8, 0x40000
	v_lshl_add_u64 v[220:221], s[8:9], 0, v[134:135]
	s_addc_u32 s53, s9, 0
	s_add_i32 s56, s85, s66
	global_load_lds_dwordx4 v[220:221], off
	v_lshl_add_u64 v[222:223], s[52:53], 0, v[130:131]
	s_mov_b32 m0, s56
	v_lshl_add_u64 v[224:225], s[44:45], 0, v[132:133]
	global_load_lds_dwordx4 v[222:223], off
	v_lshl_add_u64 v[222:223], s[52:53], 0, v[134:135]
	s_add_i32 m0, s56, 0x2000
	s_nop 0
	global_load_lds_dwordx4 v[222:223], off
	v_lshl_add_u64 v[222:223], s[44:45], 0, v[128:129]
	s_mov_b32 m0, s67
	s_nop 0
	global_load_lds_dwordx4 v[222:223], off
	s_mov_b32 m0, s72
	s_nop 0
	global_load_lds_dwordx4 v[224:225], off
	s_waitcnt vmcnt(8)
	s_waitcnt lgkmcnt(0)
	s_barrier
	s_setprio 1
	s_waitcnt lgkmcnt(0)
	v_mfma_f32_16x16x32_bf16 v[60:63], v[144:147], v[186:189], 0
	v_mfma_f32_16x16x32_bf16 v[56:59], v[152:155], v[186:189], 0
	v_mfma_f32_16x16x32_bf16 v[44:47], v[144:147], v[194:197], 0
	v_mfma_f32_16x16x32_bf16 v[40:43], v[152:155], v[194:197], 0
	v_mfma_f32_16x16x32_bf16 v[28:31], v[144:147], v[202:205], 0
	v_mfma_f32_16x16x32_bf16 v[24:27], v[152:155], v[202:205], 0
	v_mfma_f32_16x16x32_bf16 v[12:15], v[144:147], v[210:213], 0
	v_mfma_f32_16x16x32_bf16 v[8:11], v[152:155], v[210:213], 0
	v_mfma_f32_16x16x32_bf16 v[60:63], v[148:151], v[190:193], v[60:63]
	v_mfma_f32_16x16x32_bf16 v[56:59], v[156:159], v[190:193], v[56:59]
	v_mfma_f32_16x16x32_bf16 v[44:47], v[148:151], v[198:201], v[44:47]
	v_mfma_f32_16x16x32_bf16 v[40:43], v[156:159], v[198:201], v[40:43]
	v_mfma_f32_16x16x32_bf16 v[28:31], v[148:151], v[206:209], v[28:31]
	v_mfma_f32_16x16x32_bf16 v[24:27], v[156:159], v[206:209], v[24:27]
	v_mfma_f32_16x16x32_bf16 v[12:15], v[148:151], v[214:217], v[12:15]
	v_mfma_f32_16x16x32_bf16 v[8:11], v[156:159], v[214:217], v[8:11]
	s_setprio 0
	s_setprio 1
	v_mfma_f32_16x16x32_bf16 v[52:55], v[162:165], v[186:189], 0
	v_mfma_f32_16x16x32_bf16 v[48:51], v[178:181], v[186:189], 0
	v_mfma_f32_16x16x32_bf16 v[36:39], v[162:165], v[194:197], 0
	v_mfma_f32_16x16x32_bf16 v[32:35], v[178:181], v[194:197], 0
	v_mfma_f32_16x16x32_bf16 v[20:23], v[162:165], v[202:205], 0
	v_mfma_f32_16x16x32_bf16 v[16:19], v[178:181], v[202:205], 0
	v_mfma_f32_16x16x32_bf16 v[4:7], v[162:165], v[210:213], 0
	v_mfma_f32_16x16x32_bf16 v[0:3], v[178:181], v[210:213], 0
	v_mfma_f32_16x16x32_bf16 v[52:55], v[174:177], v[190:193], v[52:55]
	v_mfma_f32_16x16x32_bf16 v[48:51], v[182:185], v[190:193], v[48:51]
	v_mfma_f32_16x16x32_bf16 v[36:39], v[174:177], v[198:201], v[36:39]
	v_mfma_f32_16x16x32_bf16 v[32:35], v[182:185], v[198:201], v[32:35]
	v_mfma_f32_16x16x32_bf16 v[20:23], v[174:177], v[206:209], v[20:23]
	v_mfma_f32_16x16x32_bf16 v[16:19], v[182:185], v[206:209], v[16:19]
	v_mfma_f32_16x16x32_bf16 v[4:7], v[174:177], v[214:217], v[4:7]
	v_mfma_f32_16x16x32_bf16 v[0:3], v[182:185], v[214:217], v[0:3]
	s_setprio 0
	s_barrier
	s_add_i32 s52, 0, 0x18000
	s_add_i32 s53, 0, 0x1c000
	v_add_u32_e32 v156, s52, v168
	v_add_u32_e32 v173, s53, v168
	ds_read_b128 v[144:147], v156
	ds_read_b128 v[148:151], v156 offset:1024
	ds_read_b128 v[152:155], v156 offset:2048
	ds_read_b128 v[156:159], v156 offset:3072
	ds_read_b128 v[162:165], v173
	ds_read_b128 v[174:177], v173 offset:1024
	ds_read_b128 v[178:181], v173 offset:2048
	ds_read_b128 v[182:185], v173 offset:3072
	s_add_u32 s44, s44, 0x40000
	s_addc_u32 s45, s45, 0
	s_mov_b32 m0, s73
	v_lshl_add_u64 v[226:227], s[44:45], 0, v[128:129]
	ds_read_b128 v[186:189], v172 offset:32768
	ds_read_b128 v[190:193], v172 offset:33792
	ds_read_b128 v[194:197], v172 offset:34816
	ds_read_b128 v[198:201], v172 offset:35840
	ds_read_b128 v[202:205], v172 offset:36864
	ds_read_b128 v[206:209], v172 offset:37888
	ds_read_b128 v[210:213], v172 offset:38912
	ds_read_b128 v[214:217], v172 offset:39936
	global_load_lds_dwordx4 v[226:227], off
	v_lshl_add_u64 v[226:227], s[44:45], 0, v[132:133]
	s_mov_b32 m0, s74
	s_nop 0
	global_load_lds_dwordx4 v[226:227], off
	s_waitcnt vmcnt(8)
	s_waitcnt lgkmcnt(0)
	s_barrier
	s_setprio 1
	s_waitcnt lgkmcnt(0)
	v_mfma_f32_16x16x32_bf16 v[124:127], v[144:147], v[186:189], v[124:127]
	v_mfma_f32_16x16x32_bf16 v[120:123], v[152:155], v[186:189], v[120:123]
	v_mfma_f32_16x16x32_bf16 v[108:111], v[144:147], v[194:197], v[108:111]
	v_mfma_f32_16x16x32_bf16 v[104:107], v[152:155], v[194:197], v[104:107]
	v_mfma_f32_16x16x32_bf16 v[92:95], v[144:147], v[202:205], v[92:95]
	v_mfma_f32_16x16x32_bf16 v[88:91], v[152:155], v[202:205], v[88:91]
	v_mfma_f32_16x16x32_bf16 v[76:79], v[144:147], v[210:213], v[76:79]
	v_mfma_f32_16x16x32_bf16 v[72:75], v[152:155], v[210:213], v[72:75]
	v_mfma_f32_16x16x32_bf16 v[124:127], v[148:151], v[190:193], v[124:127]
	v_mfma_f32_16x16x32_bf16 v[120:123], v[156:159], v[190:193], v[120:123]
	v_mfma_f32_16x16x32_bf16 v[108:111], v[148:151], v[198:201], v[108:111]
	v_mfma_f32_16x16x32_bf16 v[104:107], v[156:159], v[198:201], v[104:107]
	v_mfma_f32_16x16x32_bf16 v[92:95], v[148:151], v[206:209], v[92:95]
	v_mfma_f32_16x16x32_bf16 v[88:91], v[156:159], v[206:209], v[88:91]
	v_mfma_f32_16x16x32_bf16 v[76:79], v[148:151], v[214:217], v[76:79]
	v_mfma_f32_16x16x32_bf16 v[72:75], v[156:159], v[214:217], v[72:75]
	s_setprio 0
	s_setprio 1
	v_mfma_f32_16x16x32_bf16 v[116:119], v[162:165], v[186:189], v[116:119]
	v_mfma_f32_16x16x32_bf16 v[112:115], v[178:181], v[186:189], v[112:115]
	v_mfma_f32_16x16x32_bf16 v[100:103], v[162:165], v[194:197], v[100:103]
	v_mfma_f32_16x16x32_bf16 v[96:99], v[178:181], v[194:197], v[96:99]
	v_mfma_f32_16x16x32_bf16 v[84:87], v[162:165], v[202:205], v[84:87]
	v_mfma_f32_16x16x32_bf16 v[80:83], v[178:181], v[202:205], v[80:83]
	v_mfma_f32_16x16x32_bf16 v[68:71], v[162:165], v[210:213], v[68:71]
	v_mfma_f32_16x16x32_bf16 v[64:67], v[178:181], v[210:213], v[64:67]
	v_mfma_f32_16x16x32_bf16 v[116:119], v[174:177], v[190:193], v[116:119]
	v_mfma_f32_16x16x32_bf16 v[112:115], v[182:185], v[190:193], v[112:115]
	v_mfma_f32_16x16x32_bf16 v[100:103], v[174:177], v[198:201], v[100:103]
	v_mfma_f32_16x16x32_bf16 v[96:99], v[182:185], v[198:201], v[96:99]
	v_mfma_f32_16x16x32_bf16 v[84:87], v[174:177], v[206:209], v[84:87]
	v_mfma_f32_16x16x32_bf16 v[80:83], v[182:185], v[206:209], v[80:83]
	v_mfma_f32_16x16x32_bf16 v[68:71], v[174:177], v[214:217], v[68:71]
	v_mfma_f32_16x16x32_bf16 v[64:67], v[182:185], v[214:217], v[64:67]
	s_setprio 0
	s_barrier
	s_add_i32 s44, s52, s66
	v_lshl_add_u64 v[218:219], v[218:219], 0, s[30:31]
	s_mov_b32 m0, s44
	ds_read_b128 v[186:189], v172 offset:49152
	ds_read_b128 v[190:193], v172 offset:50176
	ds_read_b128 v[194:197], v172 offset:51200
	ds_read_b128 v[198:201], v172 offset:52224
	ds_read_b128 v[202:205], v172 offset:53248
	ds_read_b128 v[206:209], v172 offset:54272
	ds_read_b128 v[210:213], v172 offset:55296
	ds_read_b128 v[214:217], v172 offset:56320
	global_load_lds_dwordx4 v[218:219], off
	s_add_i32 m0, s44, 0x2000
	s_add_u32 s8, s8, 0x40080
	v_lshl_add_u64 v[218:219], v[220:221], 0, s[30:31]
	s_addc_u32 s9, s9, 0
	s_add_i32 s44, s53, s66
	global_load_lds_dwordx4 v[218:219], off
	v_lshl_add_u64 v[218:219], s[8:9], 0, v[130:131]
	s_mov_b32 m0, s44
	s_nop 0
	global_load_lds_dwordx4 v[218:219], off
	v_lshl_add_u64 v[218:219], s[8:9], 0, v[134:135]
	s_add_i32 m0, s44, 0x2000
	s_nop 0
	global_load_lds_dwordx4 v[218:219], off
	v_lshl_add_u64 v[218:219], v[222:223], 0, s[30:31]
	s_mov_b32 m0, s77
	s_nop 0
	global_load_lds_dwordx4 v[218:219], off
	v_lshl_add_u64 v[218:219], v[224:225], 0, s[30:31]
	s_mov_b32 m0, s78
	s_nop 0
	global_load_lds_dwordx4 v[218:219], off
	s_waitcnt vmcnt(8)
	s_waitcnt lgkmcnt(0)
	s_barrier
	s_setprio 1
	s_waitcnt lgkmcnt(0)
	v_mfma_f32_16x16x32_bf16 v[60:63], v[144:147], v[186:189], v[60:63]
	v_mfma_f32_16x16x32_bf16 v[56:59], v[152:155], v[186:189], v[56:59]
	v_mfma_f32_16x16x32_bf16 v[44:47], v[144:147], v[194:197], v[44:47]
	v_mfma_f32_16x16x32_bf16 v[40:43], v[152:155], v[194:197], v[40:43]
	v_mfma_f32_16x16x32_bf16 v[28:31], v[144:147], v[202:205], v[28:31]
	v_mfma_f32_16x16x32_bf16 v[24:27], v[152:155], v[202:205], v[24:27]
	v_mfma_f32_16x16x32_bf16 v[12:15], v[144:147], v[210:213], v[12:15]
	v_mfma_f32_16x16x32_bf16 v[8:11], v[152:155], v[210:213], v[8:11]
	v_mfma_f32_16x16x32_bf16 v[60:63], v[148:151], v[190:193], v[60:63]
	v_mfma_f32_16x16x32_bf16 v[56:59], v[156:159], v[190:193], v[56:59]
	v_mfma_f32_16x16x32_bf16 v[44:47], v[148:151], v[198:201], v[44:47]
	v_mfma_f32_16x16x32_bf16 v[40:43], v[156:159], v[198:201], v[40:43]
	v_mfma_f32_16x16x32_bf16 v[28:31], v[148:151], v[206:209], v[28:31]
	v_mfma_f32_16x16x32_bf16 v[24:27], v[156:159], v[206:209], v[24:27]
	v_mfma_f32_16x16x32_bf16 v[12:15], v[148:151], v[214:217], v[12:15]
	v_mfma_f32_16x16x32_bf16 v[8:11], v[156:159], v[214:217], v[8:11]
	s_setprio 0
	s_setprio 1
	v_mfma_f32_16x16x32_bf16 v[52:55], v[162:165], v[186:189], v[52:55]
	v_mfma_f32_16x16x32_bf16 v[48:51], v[178:181], v[186:189], v[48:51]
	v_mfma_f32_16x16x32_bf16 v[36:39], v[162:165], v[194:197], v[36:39]
	v_mfma_f32_16x16x32_bf16 v[32:35], v[178:181], v[194:197], v[32:35]
	v_mfma_f32_16x16x32_bf16 v[20:23], v[162:165], v[202:205], v[20:23]
	v_mfma_f32_16x16x32_bf16 v[16:19], v[178:181], v[202:205], v[16:19]
	v_mfma_f32_16x16x32_bf16 v[4:7], v[162:165], v[210:213], v[4:7]
	v_mfma_f32_16x16x32_bf16 v[0:3], v[178:181], v[210:213], v[0:3]
	v_mfma_f32_16x16x32_bf16 v[52:55], v[174:177], v[190:193], v[52:55]
	v_mfma_f32_16x16x32_bf16 v[48:51], v[182:185], v[190:193], v[48:51]
	v_mfma_f32_16x16x32_bf16 v[36:39], v[174:177], v[198:201], v[36:39]
	v_mfma_f32_16x16x32_bf16 v[32:35], v[182:185], v[198:201], v[32:35]
	v_mfma_f32_16x16x32_bf16 v[20:23], v[174:177], v[206:209], v[20:23]
	v_mfma_f32_16x16x32_bf16 v[16:19], v[182:185], v[206:209], v[16:19]
	v_mfma_f32_16x16x32_bf16 v[4:7], v[174:177], v[214:217], v[4:7]
	v_mfma_f32_16x16x32_bf16 v[0:3], v[182:185], v[214:217], v[0:3]
	s_setprio 0
	s_barrier
	s_add_i32 s47, s47, 2
	s_add_u32 s0, s0, 0x100
	s_addc_u32 s1, s1, 0
	s_add_u32 s39, s39, 0x100
	s_addc_u32 s46, s46, 0
	s_cmp_gt_u32 s47, 13
	s_cbranch_scc0 .LBB0_229
	s_branch .Lpeel_exit_1

.Lpeel_exit_1:
	s_and_b64 vcc, exec, s[34:35]
	s_cbranch_vccz .LBB0_232
	s_barrier

.LBB0_550:
	s_add_u32 s59, s16, 0x100
	s_addc_u32 s60, s17, 0
	s_mov_b32 s61, -2
	s_waitcnt lgkmcnt(0)
	s_waitcnt vmcnt(0)
	ds_read_b128 v[128:131], v188
	ds_read_b128 v[132:135], v188 offset:1024
	ds_read_b128 v[136:139], v188 offset:2048
	ds_read_b128 v[140:143], v188 offset:3072
	ds_read_b128 v[144:147], v189
	ds_read_b128 v[148:151], v189 offset:1024
	ds_read_b128 v[152:155], v189 offset:2048
	ds_read_b128 v[156:159], v189 offset:3072
	s_add_u32 s16, s0, 0x100
	s_addc_u32 s17, s1, 0
	s_cmp_eq_u32 s61, 16
	s_cselect_b32 s35, s7, s17
	s_cselect_b32 s34, s6, s16
	s_cselect_b32 s29, s15, s60
	s_cselect_b32 s28, s14, s59
	v_lshl_add_u64 v[220:221], s[0:1], 0, v[170:171]
	s_add_i32 m0, s39, 0xc000
	ds_read_b128 v[178:181], v190
	ds_read_b128 v[192:195], v190 offset:1024
	ds_read_b128 v[196:199], v190 offset:2048
	ds_read_b128 v[200:203], v190 offset:3072
	ds_read_b128 v[204:207], v190 offset:4096
	ds_read_b128 v[208:211], v190 offset:5120
	ds_read_b128 v[212:215], v190 offset:6144
	ds_read_b128 v[216:219], v190 offset:7168
	global_load_lds_dwordx4 v[220:221], off
	v_lshl_add_u64 v[220:221], s[0:1], 0, v[172:173]
	s_add_i32 m0, s39, 0xe000
	s_nop 0
	global_load_lds_dwordx4 v[220:221], off
	s_waitcnt vmcnt(8)
	s_waitcnt lgkmcnt(0)
	s_barrier
	s_setprio 1
	s_waitcnt lgkmcnt(0)
	v_mfma_f32_16x16x32_bf16 v[124:127], v[128:131], v[178:181], 0
	v_mfma_f32_16x16x32_bf16 v[120:123], v[136:139], v[178:181], 0
	v_mfma_f32_16x16x32_bf16 v[108:111], v[128:131], v[196:199], 0
	v_mfma_f32_16x16x32_bf16 v[104:107], v[136:139], v[196:199], 0
	v_mfma_f32_16x16x32_bf16 v[92:95], v[128:131], v[204:207], 0
	v_mfma_f32_16x16x32_bf16 v[88:91], v[136:139], v[204:207], 0
	v_mfma_f32_16x16x32_bf16 v[76:79], v[128:131], v[212:215], 0
	v_mfma_f32_16x16x32_bf16 v[72:75], v[136:139], v[212:215], 0
	v_mfma_f32_16x16x32_bf16 v[124:127], v[132:135], v[192:195], v[124:127]
	v_mfma_f32_16x16x32_bf16 v[120:123], v[140:143], v[192:195], v[120:123]
	v_mfma_f32_16x16x32_bf16 v[108:111], v[132:135], v[200:203], v[108:111]
	v_mfma_f32_16x16x32_bf16 v[104:107], v[140:143], v[200:203], v[104:107]
	v_mfma_f32_16x16x32_bf16 v[92:95], v[132:135], v[208:211], v[92:95]
	v_mfma_f32_16x16x32_bf16 v[88:91], v[140:143], v[208:211], v[88:91]
	v_mfma_f32_16x16x32_bf16 v[76:79], v[132:135], v[216:219], v[76:79]
	v_mfma_f32_16x16x32_bf16 v[72:75], v[140:143], v[216:219], v[72:75]
	s_setprio 0
	s_setprio 1
	v_mfma_f32_16x16x32_bf16 v[116:119], v[144:147], v[178:181], 0
	v_mfma_f32_16x16x32_bf16 v[112:115], v[152:155], v[178:181], 0
	v_mfma_f32_16x16x32_bf16 v[100:103], v[144:147], v[196:199], 0
	v_mfma_f32_16x16x32_bf16 v[96:99], v[152:155], v[196:199], 0
	v_mfma_f32_16x16x32_bf16 v[84:87], v[144:147], v[204:207], 0
	v_mfma_f32_16x16x32_bf16 v[80:83], v[152:155], v[204:207], 0
	v_mfma_f32_16x16x32_bf16 v[68:71], v[144:147], v[212:215], 0
	v_mfma_f32_16x16x32_bf16 v[64:67], v[152:155], v[212:215], 0
	v_mfma_f32_16x16x32_bf16 v[116:119], v[148:151], v[192:195], v[116:119]
	v_mfma_f32_16x16x32_bf16 v[112:115], v[156:159], v[192:195], v[112:115]
	v_mfma_f32_16x16x32_bf16 v[100:103], v[148:151], v[200:203], v[100:103]
	v_mfma_f32_16x16x32_bf16 v[96:99], v[156:159], v[200:203], v[96:99]
	v_mfma_f32_16x16x32_bf16 v[84:87], v[148:151], v[208:211], v[84:87]
	v_mfma_f32_16x16x32_bf16 v[80:83], v[156:159], v[208:211], v[80:83]
	v_mfma_f32_16x16x32_bf16 v[68:71], v[148:151], v[216:219], v[68:71]
	v_mfma_f32_16x16x32_bf16 v[64:67], v[156:159], v[216:219], v[64:67]
	s_setprio 0
	s_barrier
	s_add_i32 s0, s50, s38
	v_lshl_add_u64 v[220:221], s[28:29], 0, v[164:165]
	s_mov_b32 m0, s0
	ds_read_b128 v[178:181], v190 offset:16384
	ds_read_b128 v[192:195], v190 offset:17408
	ds_read_b128 v[196:199], v190 offset:18432
	ds_read_b128 v[200:203], v190 offset:19456
	ds_read_b128 v[204:207], v190 offset:20480
	ds_read_b128 v[208:211], v190 offset:21504
	ds_read_b128 v[212:215], v190 offset:22528
	ds_read_b128 v[216:219], v190 offset:23552
	global_load_lds_dwordx4 v[220:221], off
	s_add_i32 m0, s0, 0x2000
	s_add_u32 s0, s28, 0x50000
	v_lshl_add_u64 v[222:223], s[28:29], 0, v[168:169]
	s_addc_u32 s1, s29, 0
	s_add_i32 s62, s51, s38
	global_load_lds_dwordx4 v[222:223], off
	v_lshl_add_u64 v[224:225], s[0:1], 0, v[164:165]
	s_mov_b32 m0, s62
	v_lshl_add_u64 v[226:227], s[34:35], 0, v[166:167]
	global_load_lds_dwordx4 v[224:225], off
	v_lshl_add_u64 v[224:225], s[0:1], 0, v[168:169]
	s_add_i32 m0, s62, 0x2000
	s_nop 0
	global_load_lds_dwordx4 v[224:225], off
	v_lshl_add_u64 v[224:225], s[34:35], 0, v[162:163]
	s_mov_b32 m0, s39
	s_nop 0
	global_load_lds_dwordx4 v[224:225], off
	s_mov_b32 m0, s40
	s_nop 0
	global_load_lds_dwordx4 v[226:227], off
	s_waitcnt vmcnt(8)
	s_waitcnt lgkmcnt(0)
	s_barrier
	s_setprio 1
	s_waitcnt lgkmcnt(0)
	v_mfma_f32_16x16x32_bf16 v[60:63], v[128:131], v[178:181], 0
	v_mfma_f32_16x16x32_bf16 v[56:59], v[136:139], v[178:181], 0
	v_mfma_f32_16x16x32_bf16 v[44:47], v[128:131], v[196:199], 0
	v_mfma_f32_16x16x32_bf16 v[40:43], v[136:139], v[196:199], 0
	v_mfma_f32_16x16x32_bf16 v[28:31], v[128:131], v[204:207], 0
	v_mfma_f32_16x16x32_bf16 v[24:27], v[136:139], v[204:207], 0
	v_mfma_f32_16x16x32_bf16 v[12:15], v[128:131], v[212:215], 0
	v_mfma_f32_16x16x32_bf16 v[8:11], v[136:139], v[212:215], 0
	v_mfma_f32_16x16x32_bf16 v[60:63], v[132:135], v[192:195], v[60:63]
	v_mfma_f32_16x16x32_bf16 v[56:59], v[140:143], v[192:195], v[56:59]
	v_mfma_f32_16x16x32_bf16 v[44:47], v[132:135], v[200:203], v[44:47]
	v_mfma_f32_16x16x32_bf16 v[40:43], v[140:143], v[200:203], v[40:43]
	v_mfma_f32_16x16x32_bf16 v[28:31], v[132:135], v[208:211], v[28:31]
	v_mfma_f32_16x16x32_bf16 v[24:27], v[140:143], v[208:211], v[24:27]
	v_mfma_f32_16x16x32_bf16 v[12:15], v[132:135], v[216:219], v[12:15]
	v_mfma_f32_16x16x32_bf16 v[8:11], v[140:143], v[216:219], v[8:11]
	s_setprio 0
	s_setprio 1
	v_mfma_f32_16x16x32_bf16 v[52:55], v[144:147], v[178:181], 0
	v_mfma_f32_16x16x32_bf16 v[48:51], v[152:155], v[178:181], 0
	v_mfma_f32_16x16x32_bf16 v[36:39], v[144:147], v[196:199], 0
	v_mfma_f32_16x16x32_bf16 v[32:35], v[152:155], v[196:199], 0
	v_mfma_f32_16x16x32_bf16 v[20:23], v[144:147], v[204:207], 0
	v_mfma_f32_16x16x32_bf16 v[16:19], v[152:155], v[204:207], 0
	v_mfma_f32_16x16x32_bf16 v[4:7], v[144:147], v[212:215], 0
	v_mfma_f32_16x16x32_bf16 v[0:3], v[152:155], v[212:215], 0
	v_mfma_f32_16x16x32_bf16 v[52:55], v[148:151], v[192:195], v[52:55]
	v_mfma_f32_16x16x32_bf16 v[48:51], v[156:159], v[192:195], v[48:51]
	v_mfma_f32_16x16x32_bf16 v[36:39], v[148:151], v[200:203], v[36:39]
	v_mfma_f32_16x16x32_bf16 v[32:35], v[156:159], v[200:203], v[32:35]
	v_mfma_f32_16x16x32_bf16 v[20:23], v[148:151], v[208:211], v[20:23]
	v_mfma_f32_16x16x32_bf16 v[16:19], v[156:159], v[208:211], v[16:19]
	v_mfma_f32_16x16x32_bf16 v[4:7], v[148:151], v[216:219], v[4:7]
	v_mfma_f32_16x16x32_bf16 v[0:3], v[156:159], v[216:219], v[0:3]
	s_setprio 0
	s_barrier
	s_add_i32 s62, 0, 0x18000
	s_add_i32 s63, 0, 0x1c000
	v_add_u32_e32 v140, s62, v183
	v_add_u32_e32 v156, s63, v183
	ds_read_b128 v[128:131], v140
	ds_read_b128 v[132:135], v140 offset:1024
	ds_read_b128 v[136:139], v140 offset:2048
	ds_read_b128 v[140:143], v140 offset:3072
	ds_read_b128 v[144:147], v156
	ds_read_b128 v[148:151], v156 offset:1024
	ds_read_b128 v[152:155], v156 offset:2048
	ds_read_b128 v[156:159], v156 offset:3072
	s_add_u32 s0, s34, 0x50000
	s_addc_u32 s1, s35, 0
	s_mov_b32 m0, s41
	v_lshl_add_u64 v[228:229], s[0:1], 0, v[162:163]
	ds_read_b128 v[178:181], v190 offset:32768
	ds_read_b128 v[192:195], v190 offset:33792
	ds_read_b128 v[196:199], v190 offset:34816
	ds_read_b128 v[200:203], v190 offset:35840
	ds_read_b128 v[204:207], v190 offset:36864
	ds_read_b128 v[208:211], v190 offset:37888
	ds_read_b128 v[212:215], v190 offset:38912
	ds_read_b128 v[216:219], v190 offset:39936
	global_load_lds_dwordx4 v[228:229], off
	v_lshl_add_u64 v[228:229], s[0:1], 0, v[166:167]
	s_mov_b32 m0, s42
	s_nop 0
	global_load_lds_dwordx4 v[228:229], off
	s_waitcnt vmcnt(8)
	s_waitcnt lgkmcnt(0)
	s_barrier
	s_setprio 1
	s_waitcnt lgkmcnt(0)
	v_mfma_f32_16x16x32_bf16 v[124:127], v[128:131], v[178:181], v[124:127]
	v_mfma_f32_16x16x32_bf16 v[120:123], v[136:139], v[178:181], v[120:123]
	v_mfma_f32_16x16x32_bf16 v[108:111], v[128:131], v[196:199], v[108:111]
	v_mfma_f32_16x16x32_bf16 v[104:107], v[136:139], v[196:199], v[104:107]
	v_mfma_f32_16x16x32_bf16 v[92:95], v[128:131], v[204:207], v[92:95]
	v_mfma_f32_16x16x32_bf16 v[88:91], v[136:139], v[204:207], v[88:91]
	v_mfma_f32_16x16x32_bf16 v[76:79], v[128:131], v[212:215], v[76:79]
	v_mfma_f32_16x16x32_bf16 v[72:75], v[136:139], v[212:215], v[72:75]
	v_mfma_f32_16x16x32_bf16 v[124:127], v[132:135], v[192:195], v[124:127]
	v_mfma_f32_16x16x32_bf16 v[120:123], v[140:143], v[192:195], v[120:123]
	v_mfma_f32_16x16x32_bf16 v[108:111], v[132:135], v[200:203], v[108:111]
	v_mfma_f32_16x16x32_bf16 v[104:107], v[140:143], v[200:203], v[104:107]
	v_mfma_f32_16x16x32_bf16 v[92:95], v[132:135], v[208:211], v[92:95]
	v_mfma_f32_16x16x32_bf16 v[88:91], v[140:143], v[208:211], v[88:91]
	v_mfma_f32_16x16x32_bf16 v[76:79], v[132:135], v[216:219], v[76:79]
	v_mfma_f32_16x16x32_bf16 v[72:75], v[140:143], v[216:219], v[72:75]
	s_setprio 0
	s_setprio 1
	v_mfma_f32_16x16x32_bf16 v[116:119], v[144:147], v[178:181], v[116:119]
	v_mfma_f32_16x16x32_bf16 v[112:115], v[152:155], v[178:181], v[112:115]
	v_mfma_f32_16x16x32_bf16 v[100:103], v[144:147], v[196:199], v[100:103]
	v_mfma_f32_16x16x32_bf16 v[96:99], v[152:155], v[196:199], v[96:99]
	v_mfma_f32_16x16x32_bf16 v[84:87], v[144:147], v[204:207], v[84:87]
	v_mfma_f32_16x16x32_bf16 v[80:83], v[152:155], v[204:207], v[80:83]
	v_mfma_f32_16x16x32_bf16 v[68:71], v[144:147], v[212:215], v[68:71]
	v_mfma_f32_16x16x32_bf16 v[64:67], v[152:155], v[212:215], v[64:67]
	v_mfma_f32_16x16x32_bf16 v[116:119], v[148:151], v[192:195], v[116:119]
	v_mfma_f32_16x16x32_bf16 v[112:115], v[156:159], v[192:195], v[112:115]
	v_mfma_f32_16x16x32_bf16 v[100:103], v[148:151], v[200:203], v[100:103]
	v_mfma_f32_16x16x32_bf16 v[96:99], v[156:159], v[200:203], v[96:99]
	v_mfma_f32_16x16x32_bf16 v[84:87], v[148:151], v[208:211], v[84:87]
	v_mfma_f32_16x16x32_bf16 v[80:83], v[156:159], v[208:211], v[80:83]
	v_mfma_f32_16x16x32_bf16 v[68:71], v[148:151], v[216:219], v[68:71]
	v_mfma_f32_16x16x32_bf16 v[64:67], v[156:159], v[216:219], v[64:67]
	s_setprio 0
	s_barrier
	s_add_i32 s0, s62, s38
	v_lshl_add_u64 v[220:221], v[220:221], 0, s[10:11]
	s_mov_b32 m0, s0
	ds_read_b128 v[178:181], v190 offset:49152
	ds_read_b128 v[192:195], v190 offset:50176
	ds_read_b128 v[196:199], v190 offset:51200
	ds_read_b128 v[200:203], v190 offset:52224
	ds_read_b128 v[204:207], v190 offset:53248
	ds_read_b128 v[208:211], v190 offset:54272
	ds_read_b128 v[212:215], v190 offset:55296
	ds_read_b128 v[216:219], v190 offset:56320
	global_load_lds_dwordx4 v[220:221], off
	s_add_i32 m0, s0, 0x2000
	s_add_u32 s0, s28, 0x50080
	v_lshl_add_u64 v[220:221], v[222:223], 0, s[10:11]
	s_addc_u32 s1, s29, 0
	s_add_i32 s28, s63, s38
	global_load_lds_dwordx4 v[220:221], off
	v_lshl_add_u64 v[220:221], s[0:1], 0, v[164:165]
	s_mov_b32 m0, s28
	s_nop 0
	global_load_lds_dwordx4 v[220:221], off
	v_lshl_add_u64 v[220:221], s[0:1], 0, v[168:169]
	s_add_i32 m0, s28, 0x2000
	s_nop 0
	global_load_lds_dwordx4 v[220:221], off
	v_lshl_add_u64 v[220:221], v[224:225], 0, s[10:11]
	s_mov_b32 m0, s45
	s_nop 0
	global_load_lds_dwordx4 v[220:221], off
	v_lshl_add_u64 v[220:221], v[226:227], 0, s[10:11]
	s_mov_b32 m0, s46
	s_nop 0
	global_load_lds_dwordx4 v[220:221], off
	s_waitcnt vmcnt(8)
	s_waitcnt lgkmcnt(0)
	s_barrier
	s_setprio 1
	s_waitcnt lgkmcnt(0)
	v_mfma_f32_16x16x32_bf16 v[60:63], v[128:131], v[178:181], v[60:63]
	v_mfma_f32_16x16x32_bf16 v[56:59], v[136:139], v[178:181], v[56:59]
	v_mfma_f32_16x16x32_bf16 v[44:47], v[128:131], v[196:199], v[44:47]
	v_mfma_f32_16x16x32_bf16 v[40:43], v[136:139], v[196:199], v[40:43]
	v_mfma_f32_16x16x32_bf16 v[28:31], v[128:131], v[204:207], v[28:31]
	v_mfma_f32_16x16x32_bf16 v[24:27], v[136:139], v[204:207], v[24:27]
	v_mfma_f32_16x16x32_bf16 v[12:15], v[128:131], v[212:215], v[12:15]
	v_mfma_f32_16x16x32_bf16 v[8:11], v[136:139], v[212:215], v[8:11]
	v_mfma_f32_16x16x32_bf16 v[60:63], v[132:135], v[192:195], v[60:63]
	v_mfma_f32_16x16x32_bf16 v[56:59], v[140:143], v[192:195], v[56:59]
	v_mfma_f32_16x16x32_bf16 v[44:47], v[132:135], v[200:203], v[44:47]
	v_mfma_f32_16x16x32_bf16 v[40:43], v[140:143], v[200:203], v[40:43]
	v_mfma_f32_16x16x32_bf16 v[28:31], v[132:135], v[208:211], v[28:31]
	v_mfma_f32_16x16x32_bf16 v[24:27], v[140:143], v[208:211], v[24:27]
	v_mfma_f32_16x16x32_bf16 v[12:15], v[132:135], v[216:219], v[12:15]
	v_mfma_f32_16x16x32_bf16 v[8:11], v[140:143], v[216:219], v[8:11]
	s_setprio 0
	s_setprio 1
	v_mfma_f32_16x16x32_bf16 v[52:55], v[144:147], v[178:181], v[52:55]
	v_mfma_f32_16x16x32_bf16 v[48:51], v[152:155], v[178:181], v[48:51]
	v_mfma_f32_16x16x32_bf16 v[36:39], v[144:147], v[196:199], v[36:39]
	v_mfma_f32_16x16x32_bf16 v[32:35], v[152:155], v[196:199], v[32:35]
	v_mfma_f32_16x16x32_bf16 v[20:23], v[144:147], v[204:207], v[20:23]
	v_mfma_f32_16x16x32_bf16 v[16:19], v[152:155], v[204:207], v[16:19]
	v_mfma_f32_16x16x32_bf16 v[4:7], v[144:147], v[212:215], v[4:7]
	v_mfma_f32_16x16x32_bf16 v[0:3], v[152:155], v[212:215], v[0:3]
	v_mfma_f32_16x16x32_bf16 v[52:55], v[148:151], v[192:195], v[52:55]
	v_mfma_f32_16x16x32_bf16 v[48:51], v[156:159], v[192:195], v[48:51]
	v_mfma_f32_16x16x32_bf16 v[36:39], v[148:151], v[200:203], v[36:39]
	v_mfma_f32_16x16x32_bf16 v[32:35], v[156:159], v[200:203], v[32:35]
	v_mfma_f32_16x16x32_bf16 v[20:23], v[148:151], v[208:211], v[20:23]
	v_mfma_f32_16x16x32_bf16 v[16:19], v[156:159], v[208:211], v[16:19]
	v_mfma_f32_16x16x32_bf16 v[4:7], v[148:151], v[216:219], v[4:7]
	v_mfma_f32_16x16x32_bf16 v[0:3], v[156:159], v[216:219], v[0:3]
	s_setprio 0
	s_barrier
	s_add_i32 s61, s61, 2
	s_add_u32 s59, s59, 0x100
	s_addc_u32 s60, s60, 0
	s_cmp_gt_u32 s61, 17
	s_mov_b64 s[0:1], s[16:17]
	s_cbranch_scc0 .LBB0_551
	s_branch .Lpeel_exit_2

.Lpeel_exit_2:
	s_and_b64 vcc, exec, s[12:13]
	s_cbranch_vccz .LBB0_554
	s_barrier

.LBB0_635:
	s_ashr_i32 s13, s12, 31
	s_lshl_b64 s[14:15], s[12:13], 19
	s_add_u32 s14, s64, s14
	s_addc_u32 s15, s65, s15
	s_and_b64 s[16:17], s[2:3], exec
	s_cselect_b32 s13, s15, s1
	s_cselect_b32 s48, s14, s0
	s_ashr_i32 s11, s10, 31
	s_lshl_b64 s[16:17], s[10:11], 19
	s_add_u32 s16, s36, s16
	s_addc_u32 s17, s37, s17
	s_and_b64 s[34:35], s[2:3], exec
	s_cselect_b32 s11, s17, s31
	s_cselect_b32 s49, s16, s30
	s_add_u32 s0, s0, 0x40080
	s_addc_u32 s1, s1, 0
	s_add_u32 s50, s30, 0x100
	s_addc_u32 s51, s31, 0
	s_mov_b32 s52, -2
	s_waitcnt vmcnt(0)
	ds_read_b128 v[144:147], v159
	ds_read_b128 v[148:151], v159 offset:1024
	ds_read_b128 v[152:155], v159 offset:2048
	ds_read_b128 v[166:169], v159 offset:3072
	ds_read_b128 v[170:173], v162
	ds_read_b128 v[174:177], v162 offset:1024
	ds_read_b128 v[178:181], v162 offset:2048
	ds_read_b128 v[182:185], v162 offset:3072
	s_add_u32 s30, s0, 0xfffc0080
	s_addc_u32 s31, s1, -1
	s_cmp_eq_u32 s52, 12
	s_cselect_b32 s35, s13, s31
	s_cselect_b32 s34, s48, s30
	s_cselect_b32 s31, s11, s51
	s_cselect_b32 s30, s49, s50
	v_lshl_add_u64 v[218:219], s[0:1], 0, v[136:137]
	s_add_i32 m0, s29, 0xc000
	ds_read_b128 v[186:189], v163
	ds_read_b128 v[190:193], v163 offset:1024
	ds_read_b128 v[194:197], v163 offset:2048
	ds_read_b128 v[198:201], v163 offset:3072
	ds_read_b128 v[202:205], v163 offset:4096
	ds_read_b128 v[206:209], v163 offset:5120
	ds_read_b128 v[210:213], v163 offset:6144
	ds_read_b128 v[214:217], v163 offset:7168
	global_load_lds_dwordx4 v[218:219], off
	v_lshl_add_u64 v[218:219], s[0:1], 0, v[138:139]
	s_add_i32 m0, s29, 0xe000
	s_nop 0
	global_load_lds_dwordx4 v[218:219], off
	s_waitcnt vmcnt(8)
	s_waitcnt lgkmcnt(0)
	s_barrier
	s_setprio 1
	s_waitcnt lgkmcnt(0)
	v_mfma_f32_16x16x32_bf16 v[124:127], v[144:147], v[186:189], 0
	v_mfma_f32_16x16x32_bf16 v[120:123], v[152:155], v[186:189], 0
	v_mfma_f32_16x16x32_bf16 v[116:119], v[144:147], v[194:197], 0
	v_mfma_f32_16x16x32_bf16 v[104:107], v[152:155], v[194:197], 0
	v_mfma_f32_16x16x32_bf16 v[92:95], v[144:147], v[202:205], 0
	v_mfma_f32_16x16x32_bf16 v[88:91], v[152:155], v[202:205], 0
	v_mfma_f32_16x16x32_bf16 v[76:79], v[144:147], v[210:213], 0
	v_mfma_f32_16x16x32_bf16 v[72:75], v[152:155], v[210:213], 0
	v_mfma_f32_16x16x32_bf16 v[124:127], v[148:151], v[190:193], v[124:127]
	v_mfma_f32_16x16x32_bf16 v[120:123], v[166:169], v[190:193], v[120:123]
	v_mfma_f32_16x16x32_bf16 v[116:119], v[148:151], v[198:201], v[116:119]
	v_mfma_f32_16x16x32_bf16 v[104:107], v[166:169], v[198:201], v[104:107]
	v_mfma_f32_16x16x32_bf16 v[92:95], v[148:151], v[206:209], v[92:95]
	v_mfma_f32_16x16x32_bf16 v[88:91], v[166:169], v[206:209], v[88:91]
	v_mfma_f32_16x16x32_bf16 v[76:79], v[148:151], v[214:217], v[76:79]
	v_mfma_f32_16x16x32_bf16 v[72:75], v[166:169], v[214:217], v[72:75]
	s_setprio 0
	s_setprio 1
	v_mfma_f32_16x16x32_bf16 v[112:115], v[170:173], v[186:189], 0
	v_mfma_f32_16x16x32_bf16 v[108:111], v[178:181], v[186:189], 0
	v_mfma_f32_16x16x32_bf16 v[100:103], v[170:173], v[194:197], 0
	v_mfma_f32_16x16x32_bf16 v[96:99], v[178:181], v[194:197], 0
	v_mfma_f32_16x16x32_bf16 v[84:87], v[170:173], v[202:205], 0
	v_mfma_f32_16x16x32_bf16 v[80:83], v[178:181], v[202:205], 0
	v_mfma_f32_16x16x32_bf16 v[68:71], v[170:173], v[210:213], 0
	v_mfma_f32_16x16x32_bf16 v[64:67], v[178:181], v[210:213], 0
	v_mfma_f32_16x16x32_bf16 v[112:115], v[174:177], v[190:193], v[112:115]
	v_mfma_f32_16x16x32_bf16 v[108:111], v[182:185], v[190:193], v[108:111]
	v_mfma_f32_16x16x32_bf16 v[100:103], v[174:177], v[198:201], v[100:103]
	v_mfma_f32_16x16x32_bf16 v[96:99], v[182:185], v[198:201], v[96:99]
	v_mfma_f32_16x16x32_bf16 v[84:87], v[174:177], v[206:209], v[84:87]
	v_mfma_f32_16x16x32_bf16 v[80:83], v[182:185], v[206:209], v[80:83]
	v_mfma_f32_16x16x32_bf16 v[68:71], v[174:177], v[214:217], v[68:71]
	v_mfma_f32_16x16x32_bf16 v[64:67], v[182:185], v[214:217], v[64:67]
	s_setprio 0
	s_barrier
	s_add_i32 s53, s46, s38
	v_lshl_add_u64 v[218:219], s[30:31], 0, v[132:133]
	s_mov_b32 m0, s53
	ds_read_b128 v[186:189], v163 offset:16384
	ds_read_b128 v[190:193], v163 offset:17408
	ds_read_b128 v[194:197], v163 offset:18432
	ds_read_b128 v[198:201], v163 offset:19456
	ds_read_b128 v[202:205], v163 offset:20480
	ds_read_b128 v[206:209], v163 offset:21504
	ds_read_b128 v[210:213], v163 offset:22528
	ds_read_b128 v[214:217], v163 offset:23552
	global_load_lds_dwordx4 v[218:219], off
	s_add_i32 m0, s53, 0x2000
	s_add_u32 s54, s30, 0x40000
	v_lshl_add_u64 v[220:221], s[30:31], 0, v[128:129]
	s_addc_u32 s55, s31, 0
	s_add_i32 s53, s47, s38
	global_load_lds_dwordx4 v[220:221], off
	v_lshl_add_u64 v[222:223], s[54:55], 0, v[132:133]
	s_mov_b32 m0, s53
	v_lshl_add_u64 v[224:225], s[34:35], 0, v[130:131]
	global_load_lds_dwordx4 v[222:223], off
	v_lshl_add_u64 v[222:223], s[54:55], 0, v[128:129]
	s_add_i32 m0, s53, 0x2000
	s_nop 0
	global_load_lds_dwordx4 v[222:223], off
	v_lshl_add_u64 v[222:223], s[34:35], 0, v[134:135]
	s_mov_b32 m0, s29
	s_nop 0
	global_load_lds_dwordx4 v[222:223], off
	s_mov_b32 m0, s40
	s_nop 0
	global_load_lds_dwordx4 v[224:225], off
	s_waitcnt vmcnt(8)
	s_waitcnt lgkmcnt(0)
	s_barrier
	s_setprio 1
	s_waitcnt lgkmcnt(0)
	v_mfma_f32_16x16x32_bf16 v[60:63], v[144:147], v[186:189], 0
	v_mfma_f32_16x16x32_bf16 v[56:59], v[152:155], v[186:189], 0
	v_mfma_f32_16x16x32_bf16 v[44:47], v[144:147], v[194:197], 0
	v_mfma_f32_16x16x32_bf16 v[40:43], v[152:155], v[194:197], 0
	v_mfma_f32_16x16x32_bf16 v[28:31], v[144:147], v[202:205], 0
	v_mfma_f32_16x16x32_bf16 v[24:27], v[152:155], v[202:205], 0
	v_mfma_f32_16x16x32_bf16 v[12:15], v[144:147], v[210:213], 0
	v_mfma_f32_16x16x32_bf16 v[8:11], v[152:155], v[210:213], 0
	v_mfma_f32_16x16x32_bf16 v[60:63], v[148:151], v[190:193], v[60:63]
	v_mfma_f32_16x16x32_bf16 v[56:59], v[166:169], v[190:193], v[56:59]
	v_mfma_f32_16x16x32_bf16 v[44:47], v[148:151], v[198:201], v[44:47]
	v_mfma_f32_16x16x32_bf16 v[40:43], v[166:169], v[198:201], v[40:43]
	v_mfma_f32_16x16x32_bf16 v[28:31], v[148:151], v[206:209], v[28:31]
	v_mfma_f32_16x16x32_bf16 v[24:27], v[166:169], v[206:209], v[24:27]
	v_mfma_f32_16x16x32_bf16 v[12:15], v[148:151], v[214:217], v[12:15]
	v_mfma_f32_16x16x32_bf16 v[8:11], v[166:169], v[214:217], v[8:11]
	s_setprio 0
	s_setprio 1
	v_mfma_f32_16x16x32_bf16 v[52:55], v[170:173], v[186:189], 0
	v_mfma_f32_16x16x32_bf16 v[48:51], v[178:181], v[186:189], 0
	v_mfma_f32_16x16x32_bf16 v[36:39], v[170:173], v[194:197], 0
	v_mfma_f32_16x16x32_bf16 v[32:35], v[178:181], v[194:197], 0
	v_mfma_f32_16x16x32_bf16 v[20:23], v[170:173], v[202:205], 0
	v_mfma_f32_16x16x32_bf16 v[16:19], v[178:181], v[202:205], 0
	v_mfma_f32_16x16x32_bf16 v[4:7], v[170:173], v[210:213], 0
	v_mfma_f32_16x16x32_bf16 v[0:3], v[178:181], v[210:213], 0
	v_mfma_f32_16x16x32_bf16 v[52:55], v[174:177], v[190:193], v[52:55]
	v_mfma_f32_16x16x32_bf16 v[48:51], v[182:185], v[190:193], v[48:51]
	v_mfma_f32_16x16x32_bf16 v[36:39], v[174:177], v[198:201], v[36:39]
	v_mfma_f32_16x16x32_bf16 v[32:35], v[182:185], v[198:201], v[32:35]
	v_mfma_f32_16x16x32_bf16 v[20:23], v[174:177], v[206:209], v[20:23]
	v_mfma_f32_16x16x32_bf16 v[16:19], v[182:185], v[206:209], v[16:19]
	v_mfma_f32_16x16x32_bf16 v[4:7], v[174:177], v[214:217], v[4:7]
	v_mfma_f32_16x16x32_bf16 v[0:3], v[182:185], v[214:217], v[0:3]
	s_setprio 0
	s_barrier
	s_add_i32 s53, 0, 0x18000
	v_add_u32_e32 v165, s53, v157
	s_add_i32 s54, 0, 0x1c000
	ds_read_b128 v[144:147], v165
	ds_read_b128 v[148:151], v165 offset:1024
	ds_read_b128 v[152:155], v165 offset:2048
	ds_read_b128 v[166:169], v165 offset:3072
	v_add_u32_e32 v165, s54, v157
	ds_read_b128 v[170:173], v165
	ds_read_b128 v[174:177], v165 offset:1024
	ds_read_b128 v[178:181], v165 offset:2048
	ds_read_b128 v[182:185], v165 offset:3072
	s_add_u32 s34, s34, 0x40000
	s_addc_u32 s35, s35, 0
	s_mov_b32 m0, s41
	v_lshl_add_u64 v[226:227], s[34:35], 0, v[134:135]
	ds_read_b128 v[186:189], v163 offset:32768
	ds_read_b128 v[190:193], v163 offset:33792
	ds_read_b128 v[194:197], v163 offset:34816
	ds_read_b128 v[198:201], v163 offset:35840
	ds_read_b128 v[202:205], v163 offset:36864
	ds_read_b128 v[206:209], v163 offset:37888
	ds_read_b128 v[210:213], v163 offset:38912
	ds_read_b128 v[214:217], v163 offset:39936
	global_load_lds_dwordx4 v[226:227], off
	v_lshl_add_u64 v[226:227], s[34:35], 0, v[130:131]
	s_mov_b32 m0, s42
	s_nop 0
	global_load_lds_dwordx4 v[226:227], off
	s_waitcnt vmcnt(8)
	s_waitcnt lgkmcnt(0)
	s_barrier
	s_setprio 1
	s_waitcnt lgkmcnt(0)
	v_mfma_f32_16x16x32_bf16 v[124:127], v[144:147], v[186:189], v[124:127]
	v_mfma_f32_16x16x32_bf16 v[120:123], v[152:155], v[186:189], v[120:123]
	v_mfma_f32_16x16x32_bf16 v[116:119], v[144:147], v[194:197], v[116:119]
	v_mfma_f32_16x16x32_bf16 v[104:107], v[152:155], v[194:197], v[104:107]
	v_mfma_f32_16x16x32_bf16 v[92:95], v[144:147], v[202:205], v[92:95]
	v_mfma_f32_16x16x32_bf16 v[88:91], v[152:155], v[202:205], v[88:91]
	v_mfma_f32_16x16x32_bf16 v[76:79], v[144:147], v[210:213], v[76:79]
	v_mfma_f32_16x16x32_bf16 v[72:75], v[152:155], v[210:213], v[72:75]
	v_mfma_f32_16x16x32_bf16 v[124:127], v[148:151], v[190:193], v[124:127]
	v_mfma_f32_16x16x32_bf16 v[120:123], v[166:169], v[190:193], v[120:123]
	v_mfma_f32_16x16x32_bf16 v[116:119], v[148:151], v[198:201], v[116:119]
	v_mfma_f32_16x16x32_bf16 v[104:107], v[166:169], v[198:201], v[104:107]
	v_mfma_f32_16x16x32_bf16 v[92:95], v[148:151], v[206:209], v[92:95]
	v_mfma_f32_16x16x32_bf16 v[88:91], v[166:169], v[206:209], v[88:91]
	v_mfma_f32_16x16x32_bf16 v[76:79], v[148:151], v[214:217], v[76:79]
	v_mfma_f32_16x16x32_bf16 v[72:75], v[166:169], v[214:217], v[72:75]
	s_setprio 0
	s_setprio 1
	v_mfma_f32_16x16x32_bf16 v[112:115], v[170:173], v[186:189], v[112:115]
	v_mfma_f32_16x16x32_bf16 v[108:111], v[178:181], v[186:189], v[108:111]
	v_mfma_f32_16x16x32_bf16 v[100:103], v[170:173], v[194:197], v[100:103]
	v_mfma_f32_16x16x32_bf16 v[96:99], v[178:181], v[194:197], v[96:99]
	v_mfma_f32_16x16x32_bf16 v[84:87], v[170:173], v[202:205], v[84:87]
	v_mfma_f32_16x16x32_bf16 v[80:83], v[178:181], v[202:205], v[80:83]
	v_mfma_f32_16x16x32_bf16 v[68:71], v[170:173], v[210:213], v[68:71]
	v_mfma_f32_16x16x32_bf16 v[64:67], v[178:181], v[210:213], v[64:67]
	v_mfma_f32_16x16x32_bf16 v[112:115], v[174:177], v[190:193], v[112:115]
	v_mfma_f32_16x16x32_bf16 v[108:111], v[182:185], v[190:193], v[108:111]
	v_mfma_f32_16x16x32_bf16 v[100:103], v[174:177], v[198:201], v[100:103]
	v_mfma_f32_16x16x32_bf16 v[96:99], v[182:185], v[198:201], v[96:99]
	v_mfma_f32_16x16x32_bf16 v[84:87], v[174:177], v[206:209], v[84:87]
	v_mfma_f32_16x16x32_bf16 v[80:83], v[182:185], v[206:209], v[80:83]
	v_mfma_f32_16x16x32_bf16 v[68:71], v[174:177], v[214:217], v[68:71]
	v_mfma_f32_16x16x32_bf16 v[64:67], v[182:185], v[214:217], v[64:67]
	s_setprio 0
	s_barrier
	s_add_i32 s34, s53, s38
	v_lshl_add_u64 v[218:219], v[218:219], 0, s[6:7]
	s_mov_b32 m0, s34
	ds_read_b128 v[186:189], v163 offset:49152
	ds_read_b128 v[190:193], v163 offset:50176
	ds_read_b128 v[194:197], v163 offset:51200
	ds_read_b128 v[198:201], v163 offset:52224
	ds_read_b128 v[202:205], v163 offset:53248
	ds_read_b128 v[206:209], v163 offset:54272
	ds_read_b128 v[210:213], v163 offset:55296
	ds_read_b128 v[214:217], v163 offset:56320
	global_load_lds_dwordx4 v[218:219], off
	s_add_i32 m0, s34, 0x2000
	s_add_u32 s30, s30, 0x40080
	v_lshl_add_u64 v[218:219], v[220:221], 0, s[6:7]
	s_addc_u32 s31, s31, 0
	s_add_i32 s34, s54, s38
	global_load_lds_dwordx4 v[218:219], off
	v_lshl_add_u64 v[218:219], s[30:31], 0, v[132:133]
	s_mov_b32 m0, s34
	s_nop 0
	global_load_lds_dwordx4 v[218:219], off
	v_lshl_add_u64 v[218:219], s[30:31], 0, v[128:129]
	s_add_i32 m0, s34, 0x2000
	s_nop 0
	global_load_lds_dwordx4 v[218:219], off
	v_lshl_add_u64 v[218:219], v[222:223], 0, s[6:7]
	s_mov_b32 m0, s44
	s_nop 0
	global_load_lds_dwordx4 v[218:219], off
	v_lshl_add_u64 v[218:219], v[224:225], 0, s[6:7]
	s_mov_b32 m0, s45
	s_nop 0
	global_load_lds_dwordx4 v[218:219], off
	s_waitcnt vmcnt(8)
	s_waitcnt lgkmcnt(0)
	s_barrier
	s_setprio 1
	s_waitcnt lgkmcnt(0)
	v_mfma_f32_16x16x32_bf16 v[60:63], v[144:147], v[186:189], v[60:63]
	v_mfma_f32_16x16x32_bf16 v[56:59], v[152:155], v[186:189], v[56:59]
	v_mfma_f32_16x16x32_bf16 v[44:47], v[144:147], v[194:197], v[44:47]
	v_mfma_f32_16x16x32_bf16 v[40:43], v[152:155], v[194:197], v[40:43]
	v_mfma_f32_16x16x32_bf16 v[28:31], v[144:147], v[202:205], v[28:31]
	v_mfma_f32_16x16x32_bf16 v[24:27], v[152:155], v[202:205], v[24:27]
	v_mfma_f32_16x16x32_bf16 v[12:15], v[144:147], v[210:213], v[12:15]
	v_mfma_f32_16x16x32_bf16 v[8:11], v[152:155], v[210:213], v[8:11]
	v_mfma_f32_16x16x32_bf16 v[60:63], v[148:151], v[190:193], v[60:63]
	v_mfma_f32_16x16x32_bf16 v[56:59], v[166:169], v[190:193], v[56:59]
	v_mfma_f32_16x16x32_bf16 v[44:47], v[148:151], v[198:201], v[44:47]
	v_mfma_f32_16x16x32_bf16 v[40:43], v[166:169], v[198:201], v[40:43]
	v_mfma_f32_16x16x32_bf16 v[28:31], v[148:151], v[206:209], v[28:31]
	v_mfma_f32_16x16x32_bf16 v[24:27], v[166:169], v[206:209], v[24:27]
	v_mfma_f32_16x16x32_bf16 v[12:15], v[148:151], v[214:217], v[12:15]
	v_mfma_f32_16x16x32_bf16 v[8:11], v[166:169], v[214:217], v[8:11]
	s_setprio 0
	s_setprio 1
	v_mfma_f32_16x16x32_bf16 v[52:55], v[170:173], v[186:189], v[52:55]
	v_mfma_f32_16x16x32_bf16 v[48:51], v[178:181], v[186:189], v[48:51]
	v_mfma_f32_16x16x32_bf16 v[36:39], v[170:173], v[194:197], v[36:39]
	v_mfma_f32_16x16x32_bf16 v[32:35], v[178:181], v[194:197], v[32:35]
	v_mfma_f32_16x16x32_bf16 v[20:23], v[170:173], v[202:205], v[20:23]
	v_mfma_f32_16x16x32_bf16 v[16:19], v[178:181], v[202:205], v[16:19]
	v_mfma_f32_16x16x32_bf16 v[4:7], v[170:173], v[210:213], v[4:7]
	v_mfma_f32_16x16x32_bf16 v[0:3], v[178:181], v[210:213], v[0:3]
	v_mfma_f32_16x16x32_bf16 v[52:55], v[174:177], v[190:193], v[52:55]
	v_mfma_f32_16x16x32_bf16 v[48:51], v[182:185], v[190:193], v[48:51]
	v_mfma_f32_16x16x32_bf16 v[36:39], v[174:177], v[198:201], v[36:39]
	v_mfma_f32_16x16x32_bf16 v[32:35], v[182:185], v[198:201], v[32:35]
	v_mfma_f32_16x16x32_bf16 v[20:23], v[174:177], v[206:209], v[20:23]
	v_mfma_f32_16x16x32_bf16 v[16:19], v[182:185], v[206:209], v[16:19]
	v_mfma_f32_16x16x32_bf16 v[4:7], v[174:177], v[214:217], v[4:7]
	v_mfma_f32_16x16x32_bf16 v[0:3], v[182:185], v[214:217], v[0:3]
	s_setprio 0
	s_barrier
	s_add_i32 s52, s52, 2
	s_add_u32 s0, s0, 0x100
	s_addc_u32 s1, s1, 0
	s_add_u32 s50, s50, 0x100
	s_addc_u32 s51, s51, 0
	s_cmp_gt_u32 s52, 13
	s_cbranch_scc0 .LBB0_636
	s_branch .Lpeel_exit_3

.Lpeel_exit_3:
	s_and_b64 vcc, exec, s[8:9]
	s_cbranch_vccz .LBB0_639
	s_barrier

.LBB0_710:
	s_ashr_i32 s17, s16, 31
	s_lshl_b64 s[26:27], s[16:17], 21
	s_add_u32 s26, s92, s26
	s_addc_u32 s27, s93, s27
	s_and_b64 s[28:29], s[6:7], exec
	s_cselect_b32 s17, s27, s1
	s_cselect_b32 s33, s26, s0
	s_ashr_i32 s15, s14, 31
	s_lshl_b64 s[28:29], s[14:15], 21
	s_add_u32 s28, s56, s28
	s_addc_u32 s29, s57, s29
	s_and_b64 s[38:39], s[6:7], exec
	s_cselect_b32 s15, s29, s37
	s_cselect_b32 s55, s28, s36
	s_add_u32 s0, s0, 0x100080
	s_addc_u32 s1, s1, 0
	s_add_u32 s58, s36, 0x100
	s_addc_u32 s59, s37, 0
	s_mov_b32 s60, -2
	s_waitcnt lgkmcnt(0)
	s_waitcnt vmcnt(0)
	ds_read_b128 v[128:131], v188
	ds_read_b128 v[132:135], v188 offset:1024
	ds_read_b128 v[136:139], v188 offset:2048
	ds_read_b128 v[140:143], v188 offset:3072
	ds_read_b128 v[144:147], v189
	ds_read_b128 v[148:151], v189 offset:1024
	ds_read_b128 v[152:155], v189 offset:2048
	ds_read_b128 v[156:159], v189 offset:3072
	s_add_u32 s36, s0, 0xfff00080
	s_addc_u32 s37, s1, -1
	s_cmp_eq_u32 s60, 60
	s_cselect_b32 s39, s17, s37
	s_cselect_b32 s38, s33, s36
	s_cselect_b32 s37, s15, s59
	s_cselect_b32 s36, s55, s58
	v_lshl_add_u64 v[220:221], s[0:1], 0, v[170:171]
	s_add_i32 m0, s31, 0xc000
	ds_read_b128 v[178:181], v190
	ds_read_b128 v[192:195], v190 offset:1024
	ds_read_b128 v[196:199], v190 offset:2048
	ds_read_b128 v[200:203], v190 offset:3072
	ds_read_b128 v[204:207], v190 offset:4096
	ds_read_b128 v[208:211], v190 offset:5120
	ds_read_b128 v[212:215], v190 offset:6144
	ds_read_b128 v[216:219], v190 offset:7168
	global_load_lds_dwordx4 v[220:221], off
	v_lshl_add_u64 v[220:221], s[0:1], 0, v[172:173]
	s_add_i32 m0, s31, 0xe000
	s_nop 0
	global_load_lds_dwordx4 v[220:221], off
	s_waitcnt vmcnt(8)
	s_waitcnt lgkmcnt(0)
	s_barrier
	s_setprio 1
	s_waitcnt lgkmcnt(0)
	v_mfma_f32_16x16x32_bf16 v[124:127], v[128:131], v[178:181], 0
	v_mfma_f32_16x16x32_bf16 v[120:123], v[136:139], v[178:181], 0
	v_mfma_f32_16x16x32_bf16 v[108:111], v[128:131], v[196:199], 0
	v_mfma_f32_16x16x32_bf16 v[104:107], v[136:139], v[196:199], 0
	v_mfma_f32_16x16x32_bf16 v[92:95], v[128:131], v[204:207], 0
	v_mfma_f32_16x16x32_bf16 v[88:91], v[136:139], v[204:207], 0
	v_mfma_f32_16x16x32_bf16 v[76:79], v[128:131], v[212:215], 0
	v_mfma_f32_16x16x32_bf16 v[72:75], v[136:139], v[212:215], 0
	v_mfma_f32_16x16x32_bf16 v[124:127], v[132:135], v[192:195], v[124:127]
	v_mfma_f32_16x16x32_bf16 v[120:123], v[140:143], v[192:195], v[120:123]
	v_mfma_f32_16x16x32_bf16 v[108:111], v[132:135], v[200:203], v[108:111]
	v_mfma_f32_16x16x32_bf16 v[104:107], v[140:143], v[200:203], v[104:107]
	v_mfma_f32_16x16x32_bf16 v[92:95], v[132:135], v[208:211], v[92:95]
	v_mfma_f32_16x16x32_bf16 v[88:91], v[140:143], v[208:211], v[88:91]
	v_mfma_f32_16x16x32_bf16 v[76:79], v[132:135], v[216:219], v[76:79]
	v_mfma_f32_16x16x32_bf16 v[72:75], v[140:143], v[216:219], v[72:75]
	s_setprio 0
	s_setprio 1
	v_mfma_f32_16x16x32_bf16 v[116:119], v[144:147], v[178:181], 0
	v_mfma_f32_16x16x32_bf16 v[112:115], v[152:155], v[178:181], 0
	v_mfma_f32_16x16x32_bf16 v[100:103], v[144:147], v[196:199], 0
	v_mfma_f32_16x16x32_bf16 v[96:99], v[152:155], v[196:199], 0
	v_mfma_f32_16x16x32_bf16 v[84:87], v[144:147], v[204:207], 0
	v_mfma_f32_16x16x32_bf16 v[80:83], v[152:155], v[204:207], 0
	v_mfma_f32_16x16x32_bf16 v[68:71], v[144:147], v[212:215], 0
	v_mfma_f32_16x16x32_bf16 v[64:67], v[152:155], v[212:215], 0
	v_mfma_f32_16x16x32_bf16 v[116:119], v[148:151], v[192:195], v[116:119]
	v_mfma_f32_16x16x32_bf16 v[112:115], v[156:159], v[192:195], v[112:115]
	v_mfma_f32_16x16x32_bf16 v[100:103], v[148:151], v[200:203], v[100:103]
	v_mfma_f32_16x16x32_bf16 v[96:99], v[156:159], v[200:203], v[96:99]
	v_mfma_f32_16x16x32_bf16 v[84:87], v[148:151], v[208:211], v[84:87]
	v_mfma_f32_16x16x32_bf16 v[80:83], v[156:159], v[208:211], v[80:83]
	v_mfma_f32_16x16x32_bf16 v[68:71], v[148:151], v[216:219], v[68:71]
	v_mfma_f32_16x16x32_bf16 v[64:67], v[156:159], v[216:219], v[64:67]
	s_setprio 0
	s_barrier
	s_add_i32 s61, s49, s40
	v_lshl_add_u64 v[220:221], s[36:37], 0, v[164:165]
	s_mov_b32 m0, s61
	ds_read_b128 v[178:181], v190 offset:16384
	ds_read_b128 v[192:195], v190 offset:17408
	ds_read_b128 v[196:199], v190 offset:18432
	ds_read_b128 v[200:203], v190 offset:19456
	ds_read_b128 v[204:207], v190 offset:20480
	ds_read_b128 v[208:211], v190 offset:21504
	ds_read_b128 v[212:215], v190 offset:22528
	ds_read_b128 v[216:219], v190 offset:23552
	global_load_lds_dwordx4 v[220:221], off
	s_add_i32 m0, s61, 0x2000
	s_add_u32 s62, s36, 0x100000
	v_lshl_add_u64 v[222:223], s[36:37], 0, v[168:169]
	s_addc_u32 s63, s37, 0
	s_add_i32 s61, s50, s40
	global_load_lds_dwordx4 v[222:223], off
	v_lshl_add_u64 v[224:225], s[62:63], 0, v[164:165]
	s_mov_b32 m0, s61
	v_lshl_add_u64 v[226:227], s[38:39], 0, v[166:167]
	global_load_lds_dwordx4 v[224:225], off
	v_lshl_add_u64 v[224:225], s[62:63], 0, v[168:169]
	s_add_i32 m0, s61, 0x2000
	s_nop 0
	global_load_lds_dwordx4 v[224:225], off
	v_lshl_add_u64 v[224:225], s[38:39], 0, v[162:163]
	s_mov_b32 m0, s31
	s_nop 0
	global_load_lds_dwordx4 v[224:225], off
	s_mov_b32 m0, s35
	s_nop 0
	global_load_lds_dwordx4 v[226:227], off
	s_waitcnt vmcnt(8)
	s_waitcnt lgkmcnt(0)
	s_barrier
	s_setprio 1
	s_waitcnt lgkmcnt(0)
	v_mfma_f32_16x16x32_bf16 v[60:63], v[128:131], v[178:181], 0
	v_mfma_f32_16x16x32_bf16 v[56:59], v[136:139], v[178:181], 0
	v_mfma_f32_16x16x32_bf16 v[44:47], v[128:131], v[196:199], 0
	v_mfma_f32_16x16x32_bf16 v[40:43], v[136:139], v[196:199], 0
	v_mfma_f32_16x16x32_bf16 v[28:31], v[128:131], v[204:207], 0
	v_mfma_f32_16x16x32_bf16 v[24:27], v[136:139], v[204:207], 0
	v_mfma_f32_16x16x32_bf16 v[12:15], v[128:131], v[212:215], 0
	v_mfma_f32_16x16x32_bf16 v[8:11], v[136:139], v[212:215], 0
	v_mfma_f32_16x16x32_bf16 v[60:63], v[132:135], v[192:195], v[60:63]
	v_mfma_f32_16x16x32_bf16 v[56:59], v[140:143], v[192:195], v[56:59]
	v_mfma_f32_16x16x32_bf16 v[44:47], v[132:135], v[200:203], v[44:47]
	v_mfma_f32_16x16x32_bf16 v[40:43], v[140:143], v[200:203], v[40:43]
	v_mfma_f32_16x16x32_bf16 v[28:31], v[132:135], v[208:211], v[28:31]
	v_mfma_f32_16x16x32_bf16 v[24:27], v[140:143], v[208:211], v[24:27]
	v_mfma_f32_16x16x32_bf16 v[12:15], v[132:135], v[216:219], v[12:15]
	v_mfma_f32_16x16x32_bf16 v[8:11], v[140:143], v[216:219], v[8:11]
	s_setprio 0
	s_setprio 1
	v_mfma_f32_16x16x32_bf16 v[52:55], v[144:147], v[178:181], 0
	v_mfma_f32_16x16x32_bf16 v[48:51], v[152:155], v[178:181], 0
	v_mfma_f32_16x16x32_bf16 v[36:39], v[144:147], v[196:199], 0
	v_mfma_f32_16x16x32_bf16 v[32:35], v[152:155], v[196:199], 0
	v_mfma_f32_16x16x32_bf16 v[20:23], v[144:147], v[204:207], 0
	v_mfma_f32_16x16x32_bf16 v[16:19], v[152:155], v[204:207], 0
	v_mfma_f32_16x16x32_bf16 v[4:7], v[144:147], v[212:215], 0
	v_mfma_f32_16x16x32_bf16 v[0:3], v[152:155], v[212:215], 0
	v_mfma_f32_16x16x32_bf16 v[52:55], v[148:151], v[192:195], v[52:55]
	v_mfma_f32_16x16x32_bf16 v[48:51], v[156:159], v[192:195], v[48:51]
	v_mfma_f32_16x16x32_bf16 v[36:39], v[148:151], v[200:203], v[36:39]
	v_mfma_f32_16x16x32_bf16 v[32:35], v[156:159], v[200:203], v[32:35]
	v_mfma_f32_16x16x32_bf16 v[20:23], v[148:151], v[208:211], v[20:23]
	v_mfma_f32_16x16x32_bf16 v[16:19], v[156:159], v[208:211], v[16:19]
	v_mfma_f32_16x16x32_bf16 v[4:7], v[148:151], v[216:219], v[4:7]
	v_mfma_f32_16x16x32_bf16 v[0:3], v[156:159], v[216:219], v[0:3]
	s_setprio 0
	s_barrier
	s_add_i32 s61, 0, 0x18000
	s_add_i32 s62, 0, 0x1c000
	v_add_u32_e32 v140, s61, v183
	v_add_u32_e32 v156, s62, v183
	ds_read_b128 v[128:131], v140
	ds_read_b128 v[132:135], v140 offset:1024
	ds_read_b128 v[136:139], v140 offset:2048
	ds_read_b128 v[140:143], v140 offset:3072
	ds_read_b128 v[144:147], v156
	ds_read_b128 v[148:151], v156 offset:1024
	ds_read_b128 v[152:155], v156 offset:2048
	ds_read_b128 v[156:159], v156 offset:3072
	s_add_u32 s38, s38, 0x100000
	s_addc_u32 s39, s39, 0
	s_mov_b32 m0, s41
	v_lshl_add_u64 v[228:229], s[38:39], 0, v[162:163]
	ds_read_b128 v[178:181], v190 offset:32768
	ds_read_b128 v[192:195], v190 offset:33792
	ds_read_b128 v[196:199], v190 offset:34816
	ds_read_b128 v[200:203], v190 offset:35840
	ds_read_b128 v[204:207], v190 offset:36864
	ds_read_b128 v[208:211], v190 offset:37888
	ds_read_b128 v[212:215], v190 offset:38912
	ds_read_b128 v[216:219], v190 offset:39936
	global_load_lds_dwordx4 v[228:229], off
	v_lshl_add_u64 v[228:229], s[38:39], 0, v[166:167]
	s_mov_b32 m0, s42
	s_nop 0
	global_load_lds_dwordx4 v[228:229], off
	s_waitcnt vmcnt(8)
	s_waitcnt lgkmcnt(0)
	s_barrier
	s_setprio 1
	s_waitcnt lgkmcnt(0)
	v_mfma_f32_16x16x32_bf16 v[124:127], v[128:131], v[178:181], v[124:127]
	v_mfma_f32_16x16x32_bf16 v[120:123], v[136:139], v[178:181], v[120:123]
	v_mfma_f32_16x16x32_bf16 v[108:111], v[128:131], v[196:199], v[108:111]
	v_mfma_f32_16x16x32_bf16 v[104:107], v[136:139], v[196:199], v[104:107]
	v_mfma_f32_16x16x32_bf16 v[92:95], v[128:131], v[204:207], v[92:95]
	v_mfma_f32_16x16x32_bf16 v[88:91], v[136:139], v[204:207], v[88:91]
	v_mfma_f32_16x16x32_bf16 v[76:79], v[128:131], v[212:215], v[76:79]
	v_mfma_f32_16x16x32_bf16 v[72:75], v[136:139], v[212:215], v[72:75]
	v_mfma_f32_16x16x32_bf16 v[124:127], v[132:135], v[192:195], v[124:127]
	v_mfma_f32_16x16x32_bf16 v[120:123], v[140:143], v[192:195], v[120:123]
	v_mfma_f32_16x16x32_bf16 v[108:111], v[132:135], v[200:203], v[108:111]
	v_mfma_f32_16x16x32_bf16 v[104:107], v[140:143], v[200:203], v[104:107]
	v_mfma_f32_16x16x32_bf16 v[92:95], v[132:135], v[208:211], v[92:95]
	v_mfma_f32_16x16x32_bf16 v[88:91], v[140:143], v[208:211], v[88:91]
	v_mfma_f32_16x16x32_bf16 v[76:79], v[132:135], v[216:219], v[76:79]
	v_mfma_f32_16x16x32_bf16 v[72:75], v[140:143], v[216:219], v[72:75]
	s_setprio 0
	s_setprio 1
	v_mfma_f32_16x16x32_bf16 v[116:119], v[144:147], v[178:181], v[116:119]
	v_mfma_f32_16x16x32_bf16 v[112:115], v[152:155], v[178:181], v[112:115]
	v_mfma_f32_16x16x32_bf16 v[100:103], v[144:147], v[196:199], v[100:103]
	v_mfma_f32_16x16x32_bf16 v[96:99], v[152:155], v[196:199], v[96:99]
	v_mfma_f32_16x16x32_bf16 v[84:87], v[144:147], v[204:207], v[84:87]
	v_mfma_f32_16x16x32_bf16 v[80:83], v[152:155], v[204:207], v[80:83]
	v_mfma_f32_16x16x32_bf16 v[68:71], v[144:147], v[212:215], v[68:71]
	v_mfma_f32_16x16x32_bf16 v[64:67], v[152:155], v[212:215], v[64:67]
	v_mfma_f32_16x16x32_bf16 v[116:119], v[148:151], v[192:195], v[116:119]
	v_mfma_f32_16x16x32_bf16 v[112:115], v[156:159], v[192:195], v[112:115]
	v_mfma_f32_16x16x32_bf16 v[100:103], v[148:151], v[200:203], v[100:103]
	v_mfma_f32_16x16x32_bf16 v[96:99], v[156:159], v[200:203], v[96:99]
	v_mfma_f32_16x16x32_bf16 v[84:87], v[148:151], v[208:211], v[84:87]
	v_mfma_f32_16x16x32_bf16 v[80:83], v[156:159], v[208:211], v[80:83]
	v_mfma_f32_16x16x32_bf16 v[68:71], v[148:151], v[216:219], v[68:71]
	v_mfma_f32_16x16x32_bf16 v[64:67], v[156:159], v[216:219], v[64:67]
	s_setprio 0
	s_barrier
	s_add_i32 s38, s61, s40
	v_lshl_add_u64 v[220:221], v[220:221], 0, s[8:9]
	s_mov_b32 m0, s38
	ds_read_b128 v[178:181], v190 offset:49152
	ds_read_b128 v[192:195], v190 offset:50176
	ds_read_b128 v[196:199], v190 offset:51200
	ds_read_b128 v[200:203], v190 offset:52224
	ds_read_b128 v[204:207], v190 offset:53248
	ds_read_b128 v[208:211], v190 offset:54272
	ds_read_b128 v[212:215], v190 offset:55296
	ds_read_b128 v[216:219], v190 offset:56320
	global_load_lds_dwordx4 v[220:221], off
	s_add_i32 m0, s38, 0x2000
	s_add_u32 s36, s36, 0x100080
	v_lshl_add_u64 v[220:221], v[222:223], 0, s[8:9]
	s_addc_u32 s37, s37, 0
	s_add_i32 s38, s62, s40
	global_load_lds_dwordx4 v[220:221], off
	v_lshl_add_u64 v[220:221], s[36:37], 0, v[164:165]
	s_mov_b32 m0, s38
	s_nop 0
	global_load_lds_dwordx4 v[220:221], off
	v_lshl_add_u64 v[220:221], s[36:37], 0, v[168:169]
	s_add_i32 m0, s38, 0x2000
	s_nop 0
	global_load_lds_dwordx4 v[220:221], off
	v_lshl_add_u64 v[220:221], v[224:225], 0, s[8:9]
	s_mov_b32 m0, s45
	s_nop 0
	global_load_lds_dwordx4 v[220:221], off
	v_lshl_add_u64 v[220:221], v[226:227], 0, s[8:9]
	s_mov_b32 m0, s46
	s_nop 0
	global_load_lds_dwordx4 v[220:221], off
	s_waitcnt vmcnt(8)
	s_waitcnt lgkmcnt(0)
	s_barrier
	s_setprio 1
	s_waitcnt lgkmcnt(0)
	v_mfma_f32_16x16x32_bf16 v[60:63], v[128:131], v[178:181], v[60:63]
	v_mfma_f32_16x16x32_bf16 v[56:59], v[136:139], v[178:181], v[56:59]
	v_mfma_f32_16x16x32_bf16 v[44:47], v[128:131], v[196:199], v[44:47]
	v_mfma_f32_16x16x32_bf16 v[40:43], v[136:139], v[196:199], v[40:43]
	v_mfma_f32_16x16x32_bf16 v[28:31], v[128:131], v[204:207], v[28:31]
	v_mfma_f32_16x16x32_bf16 v[24:27], v[136:139], v[204:207], v[24:27]
	v_mfma_f32_16x16x32_bf16 v[12:15], v[128:131], v[212:215], v[12:15]
	v_mfma_f32_16x16x32_bf16 v[8:11], v[136:139], v[212:215], v[8:11]
	v_mfma_f32_16x16x32_bf16 v[60:63], v[132:135], v[192:195], v[60:63]
	v_mfma_f32_16x16x32_bf16 v[56:59], v[140:143], v[192:195], v[56:59]
	v_mfma_f32_16x16x32_bf16 v[44:47], v[132:135], v[200:203], v[44:47]
	v_mfma_f32_16x16x32_bf16 v[40:43], v[140:143], v[200:203], v[40:43]
	v_mfma_f32_16x16x32_bf16 v[28:31], v[132:135], v[208:211], v[28:31]
	v_mfma_f32_16x16x32_bf16 v[24:27], v[140:143], v[208:211], v[24:27]
	v_mfma_f32_16x16x32_bf16 v[12:15], v[132:135], v[216:219], v[12:15]
	v_mfma_f32_16x16x32_bf16 v[8:11], v[140:143], v[216:219], v[8:11]
	s_setprio 0
	s_setprio 1
	v_mfma_f32_16x16x32_bf16 v[52:55], v[144:147], v[178:181], v[52:55]
	v_mfma_f32_16x16x32_bf16 v[48:51], v[152:155], v[178:181], v[48:51]
	v_mfma_f32_16x16x32_bf16 v[36:39], v[144:147], v[196:199], v[36:39]
	v_mfma_f32_16x16x32_bf16 v[32:35], v[152:155], v[196:199], v[32:35]
	v_mfma_f32_16x16x32_bf16 v[20:23], v[144:147], v[204:207], v[20:23]
	v_mfma_f32_16x16x32_bf16 v[16:19], v[152:155], v[204:207], v[16:19]
	v_mfma_f32_16x16x32_bf16 v[4:7], v[144:147], v[212:215], v[4:7]
	v_mfma_f32_16x16x32_bf16 v[0:3], v[152:155], v[212:215], v[0:3]
	v_mfma_f32_16x16x32_bf16 v[52:55], v[148:151], v[192:195], v[52:55]
	v_mfma_f32_16x16x32_bf16 v[48:51], v[156:159], v[192:195], v[48:51]
	v_mfma_f32_16x16x32_bf16 v[36:39], v[148:151], v[200:203], v[36:39]
	v_mfma_f32_16x16x32_bf16 v[32:35], v[156:159], v[200:203], v[32:35]
	v_mfma_f32_16x16x32_bf16 v[20:23], v[148:151], v[208:211], v[20:23]
	v_mfma_f32_16x16x32_bf16 v[16:19], v[156:159], v[208:211], v[16:19]
	v_mfma_f32_16x16x32_bf16 v[4:7], v[148:151], v[216:219], v[4:7]
	v_mfma_f32_16x16x32_bf16 v[0:3], v[156:159], v[216:219], v[0:3]
	s_setprio 0
	s_barrier
	s_add_i32 s60, s60, 2
	s_add_u32 s0, s0, 0x100
	s_addc_u32 s1, s1, 0
	s_add_u32 s58, s58, 0x100
	s_addc_u32 s59, s59, 0
	s_cmp_gt_u32 s60, 61
	s_cbranch_scc0 .LBB0_711
	s_branch .Lpeel_exit_4

.LBB0_798:
	s_ashr_i32 s29, s28, 31
	s_lshl_b64 s[30:31], s[28:29], 19
	s_add_u32 s30, s96, s30
	s_addc_u32 s31, s97, s31
	s_and_b64 s[34:35], s[4:5], exec
	s_cselect_b32 s3, s31, s1
	s_cselect_b32 s7, s30, s0
	s_ashr_i32 s27, s26, 31
	s_lshl_b64 s[34:35], s[26:27], 19
	s_add_u32 s34, s58, s34
	s_addc_u32 s35, s59, s35
	s_and_b64 s[36:37], s[4:5], exec
	s_cselect_b32 s27, s35, s9
	s_cselect_b32 s29, s34, s8
	s_add_u32 s0, s0, 0x40080
	s_addc_u32 s1, s1, 0
	s_add_u32 s33, s8, 0x100
	s_addc_u32 s38, s9, 0
	s_mov_b32 s39, -2
	s_waitcnt vmcnt(0)
	ds_read_b128 v[128:131], v177
	ds_read_b128 v[154:157], v177 offset:1024
	ds_read_b128 v[162:165], v177 offset:2048
	ds_read_b128 v[166:169], v177 offset:3072
	ds_read_b128 v[182:185], v178
	ds_read_b128 v[186:189], v178 offset:1024
	ds_read_b128 v[190:193], v178 offset:2048
	ds_read_b128 v[194:197], v178 offset:3072
	s_add_u32 s8, s0, 0xfffc0080
	s_addc_u32 s9, s1, -1
	s_cmp_eq_u32 s39, 12
	s_cselect_b32 s37, s3, s9
	s_cselect_b32 s36, s7, s8
	s_cselect_b32 s9, s27, s38
	s_cselect_b32 s8, s29, s33
	v_lshl_add_u64 v[158:159], s[0:1], 0, v[146:147]
	s_add_i32 m0, s62, 0xc000
	ds_read_b128 v[198:201], v179
	ds_read_b128 v[202:205], v179 offset:1024
	ds_read_b128 v[206:209], v179 offset:2048
	ds_read_b128 v[210:213], v179 offset:3072
	ds_read_b128 v[214:217], v179 offset:4096
	ds_read_b128 v[218:221], v179 offset:5120
	ds_read_b128 v[222:225], v179 offset:6144
	ds_read_b128 v[226:229], v179 offset:7168
	global_load_lds_dwordx4 v[158:159], off
	v_lshl_add_u64 v[158:159], s[0:1], 0, v[148:149]
	s_add_i32 m0, s62, 0xe000
	s_nop 0
	global_load_lds_dwordx4 v[158:159], off
	s_waitcnt vmcnt(8)
	s_waitcnt lgkmcnt(0)
	s_barrier
	s_setprio 1
	s_waitcnt lgkmcnt(0)
	v_mfma_f32_16x16x32_bf16 v[124:127], v[128:131], v[198:201], 0
	v_mfma_f32_16x16x32_bf16 v[120:123], v[162:165], v[198:201], 0
	v_mfma_f32_16x16x32_bf16 v[108:111], v[128:131], v[206:209], 0
	v_mfma_f32_16x16x32_bf16 v[104:107], v[162:165], v[206:209], 0
	v_mfma_f32_16x16x32_bf16 v[92:95], v[128:131], v[214:217], 0
	v_mfma_f32_16x16x32_bf16 v[88:91], v[162:165], v[214:217], 0
	v_mfma_f32_16x16x32_bf16 v[76:79], v[128:131], v[222:225], 0
	v_mfma_f32_16x16x32_bf16 v[72:75], v[162:165], v[222:225], 0
	v_mfma_f32_16x16x32_bf16 v[124:127], v[154:157], v[202:205], v[124:127]
	v_mfma_f32_16x16x32_bf16 v[120:123], v[166:169], v[202:205], v[120:123]
	v_mfma_f32_16x16x32_bf16 v[108:111], v[154:157], v[210:213], v[108:111]
	v_mfma_f32_16x16x32_bf16 v[104:107], v[166:169], v[210:213], v[104:107]
	v_mfma_f32_16x16x32_bf16 v[92:95], v[154:157], v[218:221], v[92:95]
	v_mfma_f32_16x16x32_bf16 v[88:91], v[166:169], v[218:221], v[88:91]
	v_mfma_f32_16x16x32_bf16 v[76:79], v[154:157], v[226:229], v[76:79]
	v_mfma_f32_16x16x32_bf16 v[72:75], v[166:169], v[226:229], v[72:75]
	s_setprio 0
	s_setprio 1
	v_mfma_f32_16x16x32_bf16 v[116:119], v[182:185], v[198:201], 0
	v_mfma_f32_16x16x32_bf16 v[112:115], v[190:193], v[198:201], 0
	v_mfma_f32_16x16x32_bf16 v[100:103], v[182:185], v[206:209], 0
	v_mfma_f32_16x16x32_bf16 v[96:99], v[190:193], v[206:209], 0
	v_mfma_f32_16x16x32_bf16 v[84:87], v[182:185], v[214:217], 0
	v_mfma_f32_16x16x32_bf16 v[80:83], v[190:193], v[214:217], 0
	v_mfma_f32_16x16x32_bf16 v[68:71], v[182:185], v[222:225], 0
	v_mfma_f32_16x16x32_bf16 v[64:67], v[190:193], v[222:225], 0
	v_mfma_f32_16x16x32_bf16 v[116:119], v[186:189], v[202:205], v[116:119]
	v_mfma_f32_16x16x32_bf16 v[112:115], v[194:197], v[202:205], v[112:115]
	v_mfma_f32_16x16x32_bf16 v[100:103], v[186:189], v[210:213], v[100:103]
	v_mfma_f32_16x16x32_bf16 v[96:99], v[194:197], v[210:213], v[96:99]
	v_mfma_f32_16x16x32_bf16 v[84:87], v[186:189], v[218:221], v[84:87]
	v_mfma_f32_16x16x32_bf16 v[80:83], v[194:197], v[218:221], v[80:83]
	v_mfma_f32_16x16x32_bf16 v[68:71], v[186:189], v[226:229], v[68:71]
	v_mfma_f32_16x16x32_bf16 v[64:67], v[194:197], v[226:229], v[64:67]
	s_setprio 0
	s_barrier
	s_add_i32 s40, s78, s61
	v_lshl_add_u64 v[158:159], s[8:9], 0, v[134:135]
	s_mov_b32 m0, s40
	ds_read_b128 v[198:201], v179 offset:16384
	ds_read_b128 v[202:205], v179 offset:17408
	ds_read_b128 v[206:209], v179 offset:18432
	ds_read_b128 v[210:213], v179 offset:19456
	ds_read_b128 v[214:217], v179 offset:20480
	ds_read_b128 v[218:221], v179 offset:21504
	ds_read_b128 v[222:225], v179 offset:22528
	ds_read_b128 v[226:229], v179 offset:23552
	global_load_lds_dwordx4 v[158:159], off
	s_add_i32 m0, s40, 0x2000
	s_add_u32 s40, s8, 0x40000
	v_lshl_add_u64 v[230:231], s[8:9], 0, v[138:139]
	s_addc_u32 s41, s9, 0
	s_add_i32 s42, s79, s61
	global_load_lds_dwordx4 v[230:231], off
	v_lshl_add_u64 v[232:233], s[40:41], 0, v[134:135]
	s_mov_b32 m0, s42
	v_lshl_add_u64 v[234:235], s[36:37], 0, v[136:137]
	global_load_lds_dwordx4 v[232:233], off
	v_lshl_add_u64 v[232:233], s[40:41], 0, v[138:139]
	s_add_i32 m0, s42, 0x2000
	s_nop 0
	global_load_lds_dwordx4 v[232:233], off
	v_lshl_add_u64 v[232:233], s[36:37], 0, v[132:133]
	s_mov_b32 m0, s62
	s_nop 0
	global_load_lds_dwordx4 v[232:233], off
	s_mov_b32 m0, s63
	s_nop 0
	global_load_lds_dwordx4 v[234:235], off
	s_waitcnt vmcnt(8)
	s_waitcnt lgkmcnt(0)
	s_barrier
	s_setprio 1
	s_waitcnt lgkmcnt(0)
	v_mfma_f32_16x16x32_bf16 v[60:63], v[128:131], v[198:201], 0
	v_mfma_f32_16x16x32_bf16 v[56:59], v[162:165], v[198:201], 0
	v_mfma_f32_16x16x32_bf16 v[44:47], v[128:131], v[206:209], 0
	v_mfma_f32_16x16x32_bf16 v[40:43], v[162:165], v[206:209], 0
	v_mfma_f32_16x16x32_bf16 v[28:31], v[128:131], v[214:217], 0
	v_mfma_f32_16x16x32_bf16 v[24:27], v[162:165], v[214:217], 0
	v_mfma_f32_16x16x32_bf16 v[12:15], v[128:131], v[222:225], 0
	v_mfma_f32_16x16x32_bf16 v[8:11], v[162:165], v[222:225], 0
	v_mfma_f32_16x16x32_bf16 v[60:63], v[154:157], v[202:205], v[60:63]
	v_mfma_f32_16x16x32_bf16 v[56:59], v[166:169], v[202:205], v[56:59]
	v_mfma_f32_16x16x32_bf16 v[44:47], v[154:157], v[210:213], v[44:47]
	v_mfma_f32_16x16x32_bf16 v[40:43], v[166:169], v[210:213], v[40:43]
	v_mfma_f32_16x16x32_bf16 v[28:31], v[154:157], v[218:221], v[28:31]
	v_mfma_f32_16x16x32_bf16 v[24:27], v[166:169], v[218:221], v[24:27]
	v_mfma_f32_16x16x32_bf16 v[12:15], v[154:157], v[226:229], v[12:15]
	v_mfma_f32_16x16x32_bf16 v[8:11], v[166:169], v[226:229], v[8:11]
	s_setprio 0
	s_setprio 1
	v_mfma_f32_16x16x32_bf16 v[52:55], v[182:185], v[198:201], 0
	v_mfma_f32_16x16x32_bf16 v[48:51], v[190:193], v[198:201], 0
	v_mfma_f32_16x16x32_bf16 v[36:39], v[182:185], v[206:209], 0
	v_mfma_f32_16x16x32_bf16 v[32:35], v[190:193], v[206:209], 0
	v_mfma_f32_16x16x32_bf16 v[20:23], v[182:185], v[214:217], 0
	v_mfma_f32_16x16x32_bf16 v[16:19], v[190:193], v[214:217], 0
	v_mfma_f32_16x16x32_bf16 v[4:7], v[182:185], v[222:225], 0
	v_mfma_f32_16x16x32_bf16 v[0:3], v[190:193], v[222:225], 0
	v_mfma_f32_16x16x32_bf16 v[52:55], v[186:189], v[202:205], v[52:55]
	v_mfma_f32_16x16x32_bf16 v[48:51], v[194:197], v[202:205], v[48:51]
	v_mfma_f32_16x16x32_bf16 v[36:39], v[186:189], v[210:213], v[36:39]
	v_mfma_f32_16x16x32_bf16 v[32:35], v[194:197], v[210:213], v[32:35]
	v_mfma_f32_16x16x32_bf16 v[20:23], v[186:189], v[218:221], v[20:23]
	v_mfma_f32_16x16x32_bf16 v[16:19], v[194:197], v[218:221], v[16:19]
	v_mfma_f32_16x16x32_bf16 v[4:7], v[186:189], v[226:229], v[4:7]
	v_mfma_f32_16x16x32_bf16 v[0:3], v[194:197], v[226:229], v[0:3]
	s_setprio 0
	s_barrier
	s_add_i32 s40, 0, 0x18000
	v_add_u32_e32 v140, s40, v171
	s_add_i32 s41, 0, 0x1c000
	ds_read_b128 v[128:131], v140
	ds_read_b128 v[154:157], v140 offset:1024
	ds_read_b128 v[162:165], v140 offset:2048
	ds_read_b128 v[166:169], v140 offset:3072
	v_add_u32_e32 v140, s41, v171
	ds_read_b128 v[182:185], v140
	ds_read_b128 v[186:189], v140 offset:1024
	ds_read_b128 v[190:193], v140 offset:2048
	ds_read_b128 v[194:197], v140 offset:3072
	s_add_u32 s36, s36, 0x40000
	s_addc_u32 s37, s37, 0
	s_mov_b32 m0, s64
	v_lshl_add_u64 v[236:237], s[36:37], 0, v[132:133]
	ds_read_b128 v[198:201], v179 offset:32768
	ds_read_b128 v[202:205], v179 offset:33792
	ds_read_b128 v[206:209], v179 offset:34816
	ds_read_b128 v[210:213], v179 offset:35840
	ds_read_b128 v[214:217], v179 offset:36864
	ds_read_b128 v[218:221], v179 offset:37888
	ds_read_b128 v[222:225], v179 offset:38912
	ds_read_b128 v[226:229], v179 offset:39936
	global_load_lds_dwordx4 v[236:237], off
	v_lshl_add_u64 v[236:237], s[36:37], 0, v[136:137]
	s_mov_b32 m0, s65
	s_nop 0
	global_load_lds_dwordx4 v[236:237], off
	s_waitcnt vmcnt(8)
	s_waitcnt lgkmcnt(0)
	s_barrier
	s_setprio 1
	s_waitcnt lgkmcnt(0)
	v_mfma_f32_16x16x32_bf16 v[124:127], v[128:131], v[198:201], v[124:127]
	v_mfma_f32_16x16x32_bf16 v[120:123], v[162:165], v[198:201], v[120:123]
	v_mfma_f32_16x16x32_bf16 v[108:111], v[128:131], v[206:209], v[108:111]
	v_mfma_f32_16x16x32_bf16 v[104:107], v[162:165], v[206:209], v[104:107]
	v_mfma_f32_16x16x32_bf16 v[92:95], v[128:131], v[214:217], v[92:95]
	v_mfma_f32_16x16x32_bf16 v[88:91], v[162:165], v[214:217], v[88:91]
	v_mfma_f32_16x16x32_bf16 v[76:79], v[128:131], v[222:225], v[76:79]
	v_mfma_f32_16x16x32_bf16 v[72:75], v[162:165], v[222:225], v[72:75]
	v_mfma_f32_16x16x32_bf16 v[124:127], v[154:157], v[202:205], v[124:127]
	v_mfma_f32_16x16x32_bf16 v[120:123], v[166:169], v[202:205], v[120:123]
	v_mfma_f32_16x16x32_bf16 v[108:111], v[154:157], v[210:213], v[108:111]
	v_mfma_f32_16x16x32_bf16 v[104:107], v[166:169], v[210:213], v[104:107]
	v_mfma_f32_16x16x32_bf16 v[92:95], v[154:157], v[218:221], v[92:95]
	v_mfma_f32_16x16x32_bf16 v[88:91], v[166:169], v[218:221], v[88:91]
	v_mfma_f32_16x16x32_bf16 v[76:79], v[154:157], v[226:229], v[76:79]
	v_mfma_f32_16x16x32_bf16 v[72:75], v[166:169], v[226:229], v[72:75]
	s_setprio 0
	s_setprio 1
	v_mfma_f32_16x16x32_bf16 v[116:119], v[182:185], v[198:201], v[116:119]
	v_mfma_f32_16x16x32_bf16 v[112:115], v[190:193], v[198:201], v[112:115]
	v_mfma_f32_16x16x32_bf16 v[100:103], v[182:185], v[206:209], v[100:103]
	v_mfma_f32_16x16x32_bf16 v[96:99], v[190:193], v[206:209], v[96:99]
	v_mfma_f32_16x16x32_bf16 v[84:87], v[182:185], v[214:217], v[84:87]
	v_mfma_f32_16x16x32_bf16 v[80:83], v[190:193], v[214:217], v[80:83]
	v_mfma_f32_16x16x32_bf16 v[68:71], v[182:185], v[222:225], v[68:71]
	v_mfma_f32_16x16x32_bf16 v[64:67], v[190:193], v[222:225], v[64:67]
	v_mfma_f32_16x16x32_bf16 v[116:119], v[186:189], v[202:205], v[116:119]
	v_mfma_f32_16x16x32_bf16 v[112:115], v[194:197], v[202:205], v[112:115]
	v_mfma_f32_16x16x32_bf16 v[100:103], v[186:189], v[210:213], v[100:103]
	v_mfma_f32_16x16x32_bf16 v[96:99], v[194:197], v[210:213], v[96:99]
	v_mfma_f32_16x16x32_bf16 v[84:87], v[186:189], v[218:221], v[84:87]
	v_mfma_f32_16x16x32_bf16 v[80:83], v[194:197], v[218:221], v[80:83]
	v_mfma_f32_16x16x32_bf16 v[68:71], v[186:189], v[226:229], v[68:71]
	v_mfma_f32_16x16x32_bf16 v[64:67], v[194:197], v[226:229], v[64:67]
	s_setprio 0
	s_barrier
	s_add_i32 s36, s40, s61
	v_lshl_add_u64 v[158:159], v[158:159], 0, s[14:15]
	s_mov_b32 m0, s36
	ds_read_b128 v[198:201], v179 offset:49152
	ds_read_b128 v[202:205], v179 offset:50176
	ds_read_b128 v[206:209], v179 offset:51200
	ds_read_b128 v[210:213], v179 offset:52224
	ds_read_b128 v[214:217], v179 offset:53248
	ds_read_b128 v[218:221], v179 offset:54272
	ds_read_b128 v[222:225], v179 offset:55296
	ds_read_b128 v[226:229], v179 offset:56320
	global_load_lds_dwordx4 v[158:159], off
	s_add_i32 m0, s36, 0x2000
	s_add_u32 s8, s8, 0x40080
	v_lshl_add_u64 v[158:159], v[230:231], 0, s[14:15]
	s_addc_u32 s9, s9, 0
	s_add_i32 s36, s41, s61
	global_load_lds_dwordx4 v[158:159], off
	v_lshl_add_u64 v[158:159], s[8:9], 0, v[134:135]
	s_mov_b32 m0, s36
	s_nop 0
	global_load_lds_dwordx4 v[158:159], off
	v_lshl_add_u64 v[158:159], s[8:9], 0, v[138:139]
	s_add_i32 m0, s36, 0x2000
	s_nop 0
	global_load_lds_dwordx4 v[158:159], off
	v_lshl_add_u64 v[158:159], v[232:233], 0, s[14:15]
	s_mov_b32 m0, s76
	s_nop 0
	global_load_lds_dwordx4 v[158:159], off
	v_lshl_add_u64 v[158:159], v[234:235], 0, s[14:15]
	s_mov_b32 m0, s77
	s_nop 0
	global_load_lds_dwordx4 v[158:159], off
	s_waitcnt vmcnt(8)
	s_waitcnt lgkmcnt(0)
	s_barrier
	s_setprio 1
	s_waitcnt lgkmcnt(0)
	v_mfma_f32_16x16x32_bf16 v[60:63], v[128:131], v[198:201], v[60:63]
	v_mfma_f32_16x16x32_bf16 v[56:59], v[162:165], v[198:201], v[56:59]
	v_mfma_f32_16x16x32_bf16 v[44:47], v[128:131], v[206:209], v[44:47]
	v_mfma_f32_16x16x32_bf16 v[40:43], v[162:165], v[206:209], v[40:43]
	v_mfma_f32_16x16x32_bf16 v[28:31], v[128:131], v[214:217], v[28:31]
	v_mfma_f32_16x16x32_bf16 v[24:27], v[162:165], v[214:217], v[24:27]
	v_mfma_f32_16x16x32_bf16 v[12:15], v[128:131], v[222:225], v[12:15]
	v_mfma_f32_16x16x32_bf16 v[8:11], v[162:165], v[222:225], v[8:11]
	v_mfma_f32_16x16x32_bf16 v[60:63], v[154:157], v[202:205], v[60:63]
	v_mfma_f32_16x16x32_bf16 v[56:59], v[166:169], v[202:205], v[56:59]
	v_mfma_f32_16x16x32_bf16 v[44:47], v[154:157], v[210:213], v[44:47]
	v_mfma_f32_16x16x32_bf16 v[40:43], v[166:169], v[210:213], v[40:43]
	v_mfma_f32_16x16x32_bf16 v[28:31], v[154:157], v[218:221], v[28:31]
	v_mfma_f32_16x16x32_bf16 v[24:27], v[166:169], v[218:221], v[24:27]
	v_mfma_f32_16x16x32_bf16 v[12:15], v[154:157], v[226:229], v[12:15]
	v_mfma_f32_16x16x32_bf16 v[8:11], v[166:169], v[226:229], v[8:11]
	s_setprio 0
	s_setprio 1
	v_mfma_f32_16x16x32_bf16 v[52:55], v[182:185], v[198:201], v[52:55]
	v_mfma_f32_16x16x32_bf16 v[48:51], v[190:193], v[198:201], v[48:51]
	v_mfma_f32_16x16x32_bf16 v[36:39], v[182:185], v[206:209], v[36:39]
	v_mfma_f32_16x16x32_bf16 v[32:35], v[190:193], v[206:209], v[32:35]
	v_mfma_f32_16x16x32_bf16 v[20:23], v[182:185], v[214:217], v[20:23]
	v_mfma_f32_16x16x32_bf16 v[16:19], v[190:193], v[214:217], v[16:19]
	v_mfma_f32_16x16x32_bf16 v[4:7], v[182:185], v[222:225], v[4:7]
	v_mfma_f32_16x16x32_bf16 v[0:3], v[190:193], v[222:225], v[0:3]
	v_mfma_f32_16x16x32_bf16 v[52:55], v[186:189], v[202:205], v[52:55]
	v_mfma_f32_16x16x32_bf16 v[48:51], v[194:197], v[202:205], v[48:51]
	v_mfma_f32_16x16x32_bf16 v[36:39], v[186:189], v[210:213], v[36:39]
	v_mfma_f32_16x16x32_bf16 v[32:35], v[194:197], v[210:213], v[32:35]
	v_mfma_f32_16x16x32_bf16 v[20:23], v[186:189], v[218:221], v[20:23]
	v_mfma_f32_16x16x32_bf16 v[16:19], v[194:197], v[218:221], v[16:19]
	v_mfma_f32_16x16x32_bf16 v[4:7], v[186:189], v[226:229], v[4:7]
	v_mfma_f32_16x16x32_bf16 v[0:3], v[194:197], v[226:229], v[0:3]
	s_setprio 0
	s_barrier
	s_add_i32 s39, s39, 2
	s_add_u32 s0, s0, 0x100
	s_addc_u32 s1, s1, 0
	s_add_u32 s33, s33, 0x100
	s_addc_u32 s38, s38, 0
	s_cmp_gt_u32 s39, 13
	s_cbranch_scc0 .LBB0_799
	s_branch .Lpeel_exit_5

.Lpeel_exit_5:
	s_and_b64 vcc, exec, s[16:17]
	s_cbranch_vccz .LBB0_802
	s_barrier

.LBB0_1402:
	s_ashr_i32 s17, s16, 31
	s_lshl_b64 s[18:19], s[16:17], 19
	s_add_u32 s18, s76, s18
	s_addc_u32 s19, s78, s19
	s_and_b64 s[20:21], s[6:7], exec
	s_cselect_b32 s17, s19, s1
	s_cselect_b32 s33, s18, s0
	s_ashr_i32 s15, s14, 31
	s_lshl_b64 s[20:21], s[14:15], 19
	s_add_u32 s20, s31, s20
	s_addc_u32 s21, s34, s21
	s_and_b64 s[28:29], s[6:7], exec
	s_cselect_b32 s15, s21, s27
	s_cselect_b32 s50, s20, s26
	s_add_u32 s0, s0, 0x40080
	s_addc_u32 s1, s1, 0
	s_add_u32 s51, s26, 0x100
	s_addc_u32 s52, s27, 0
	s_mov_b32 s53, -2
	s_waitcnt lgkmcnt(0)
	ds_read_b128 v[128:131], v193
	ds_read_b128 v[132:135], v193 offset:1024
	ds_read_b128 v[136:139], v193 offset:2048
	ds_read_b128 v[140:143], v193 offset:3072
	ds_read_b128 v[144:147], v194
	ds_read_b128 v[148:151], v194 offset:1024
	ds_read_b128 v[152:155], v194 offset:2048
	ds_read_b128 v[156:159], v194 offset:3072
	s_add_u32 s26, s0, 0xfffc0080
	s_addc_u32 s27, s1, -1
	s_cmp_eq_u32 s53, 12
	s_cselect_b32 s29, s17, s27
	s_cselect_b32 s28, s33, s26
	s_cselect_b32 s27, s15, s52
	s_cselect_b32 s26, s50, s51
	v_lshl_add_u64 v[224:225], s[0:1], 0, v[170:171]
	s_add_i32 m0, s23, 0xc000
	ds_read_b128 v[178:181], v195
	ds_read_b128 v[196:199], v195 offset:1024
	ds_read_b128 v[200:203], v195 offset:2048
	ds_read_b128 v[204:207], v195 offset:3072
	ds_read_b128 v[208:211], v195 offset:4096
	ds_read_b128 v[212:215], v195 offset:5120
	ds_read_b128 v[216:219], v195 offset:6144
	ds_read_b128 v[220:223], v195 offset:7168
	global_load_lds_dwordx4 v[224:225], off
	v_lshl_add_u64 v[224:225], s[0:1], 0, v[172:173]
	s_add_i32 m0, s23, 0xe000
	s_nop 0
	global_load_lds_dwordx4 v[224:225], off
	s_waitcnt vmcnt(8)
	s_waitcnt lgkmcnt(0)
	s_barrier
	s_setprio 1
	s_waitcnt lgkmcnt(0)
	v_mfma_f32_16x16x32_bf16 v[124:127], v[128:131], v[178:181], 0
	v_mfma_f32_16x16x32_bf16 v[120:123], v[136:139], v[178:181], 0
	v_mfma_f32_16x16x32_bf16 v[108:111], v[128:131], v[200:203], 0
	v_mfma_f32_16x16x32_bf16 v[104:107], v[136:139], v[200:203], 0
	v_mfma_f32_16x16x32_bf16 v[92:95], v[128:131], v[208:211], 0
	v_mfma_f32_16x16x32_bf16 v[88:91], v[136:139], v[208:211], 0
	v_mfma_f32_16x16x32_bf16 v[76:79], v[128:131], v[216:219], 0
	v_mfma_f32_16x16x32_bf16 v[72:75], v[136:139], v[216:219], 0
	v_mfma_f32_16x16x32_bf16 v[124:127], v[132:135], v[196:199], v[124:127]
	v_mfma_f32_16x16x32_bf16 v[120:123], v[140:143], v[196:199], v[120:123]
	v_mfma_f32_16x16x32_bf16 v[108:111], v[132:135], v[204:207], v[108:111]
	v_mfma_f32_16x16x32_bf16 v[104:107], v[140:143], v[204:207], v[104:107]
	v_mfma_f32_16x16x32_bf16 v[92:95], v[132:135], v[212:215], v[92:95]
	v_mfma_f32_16x16x32_bf16 v[88:91], v[140:143], v[212:215], v[88:91]
	v_mfma_f32_16x16x32_bf16 v[76:79], v[132:135], v[220:223], v[76:79]
	v_mfma_f32_16x16x32_bf16 v[72:75], v[140:143], v[220:223], v[72:75]
	s_setprio 0
	s_setprio 1
	v_mfma_f32_16x16x32_bf16 v[116:119], v[144:147], v[178:181], 0
	v_mfma_f32_16x16x32_bf16 v[112:115], v[152:155], v[178:181], 0
	v_mfma_f32_16x16x32_bf16 v[100:103], v[144:147], v[200:203], 0
	v_mfma_f32_16x16x32_bf16 v[96:99], v[152:155], v[200:203], 0
	v_mfma_f32_16x16x32_bf16 v[84:87], v[144:147], v[208:211], 0
	v_mfma_f32_16x16x32_bf16 v[80:83], v[152:155], v[208:211], 0
	v_mfma_f32_16x16x32_bf16 v[68:71], v[144:147], v[216:219], 0
	v_mfma_f32_16x16x32_bf16 v[64:67], v[152:155], v[216:219], 0
	v_mfma_f32_16x16x32_bf16 v[116:119], v[148:151], v[196:199], v[116:119]
	v_mfma_f32_16x16x32_bf16 v[112:115], v[156:159], v[196:199], v[112:115]
	v_mfma_f32_16x16x32_bf16 v[100:103], v[148:151], v[204:207], v[100:103]
	v_mfma_f32_16x16x32_bf16 v[96:99], v[156:159], v[204:207], v[96:99]
	v_mfma_f32_16x16x32_bf16 v[84:87], v[148:151], v[212:215], v[84:87]
	v_mfma_f32_16x16x32_bf16 v[80:83], v[156:159], v[212:215], v[80:83]
	v_mfma_f32_16x16x32_bf16 v[68:71], v[148:151], v[220:223], v[68:71]
	v_mfma_f32_16x16x32_bf16 v[64:67], v[156:159], v[220:223], v[64:67]
	s_setprio 0
	s_barrier
	s_add_i32 s54, s44, s35
	v_lshl_add_u64 v[224:225], s[26:27], 0, v[164:165]
	s_mov_b32 m0, s54
	ds_read_b128 v[178:181], v195 offset:16384
	ds_read_b128 v[196:199], v195 offset:17408
	ds_read_b128 v[200:203], v195 offset:18432
	ds_read_b128 v[204:207], v195 offset:19456
	ds_read_b128 v[208:211], v195 offset:20480
	ds_read_b128 v[212:215], v195 offset:21504
	ds_read_b128 v[216:219], v195 offset:22528
	ds_read_b128 v[220:223], v195 offset:23552
	global_load_lds_dwordx4 v[224:225], off
	s_add_i32 m0, s54, 0x2000
	s_add_u32 s54, s26, 0x40000
	v_lshl_add_u64 v[226:227], s[26:27], 0, v[168:169]
	s_addc_u32 s55, s27, 0
	s_add_i32 s56, s45, s35
	global_load_lds_dwordx4 v[226:227], off
	v_lshl_add_u64 v[228:229], s[54:55], 0, v[164:165]
	s_mov_b32 m0, s56
	v_lshl_add_u64 v[230:231], s[28:29], 0, v[166:167]
	global_load_lds_dwordx4 v[228:229], off
	v_lshl_add_u64 v[228:229], s[54:55], 0, v[168:169]
	s_add_i32 m0, s56, 0x2000
	s_nop 0
	global_load_lds_dwordx4 v[228:229], off
	v_lshl_add_u64 v[228:229], s[28:29], 0, v[162:163]
	s_mov_b32 m0, s23
	s_nop 0
	global_load_lds_dwordx4 v[228:229], off
	s_mov_b32 m0, s25
	s_nop 0
	global_load_lds_dwordx4 v[230:231], off
	s_waitcnt vmcnt(8)
	s_waitcnt lgkmcnt(0)
	s_barrier
	s_setprio 1
	s_waitcnt lgkmcnt(0)
	v_mfma_f32_16x16x32_bf16 v[60:63], v[128:131], v[178:181], 0
	v_mfma_f32_16x16x32_bf16 v[56:59], v[136:139], v[178:181], 0
	v_mfma_f32_16x16x32_bf16 v[44:47], v[128:131], v[200:203], 0
	v_mfma_f32_16x16x32_bf16 v[40:43], v[136:139], v[200:203], 0
	v_mfma_f32_16x16x32_bf16 v[28:31], v[128:131], v[208:211], 0
	v_mfma_f32_16x16x32_bf16 v[24:27], v[136:139], v[208:211], 0
	v_mfma_f32_16x16x32_bf16 v[12:15], v[128:131], v[216:219], 0
	v_mfma_f32_16x16x32_bf16 v[8:11], v[136:139], v[216:219], 0
	v_mfma_f32_16x16x32_bf16 v[60:63], v[132:135], v[196:199], v[60:63]
	v_mfma_f32_16x16x32_bf16 v[56:59], v[140:143], v[196:199], v[56:59]
	v_mfma_f32_16x16x32_bf16 v[44:47], v[132:135], v[204:207], v[44:47]
	v_mfma_f32_16x16x32_bf16 v[40:43], v[140:143], v[204:207], v[40:43]
	v_mfma_f32_16x16x32_bf16 v[28:31], v[132:135], v[212:215], v[28:31]
	v_mfma_f32_16x16x32_bf16 v[24:27], v[140:143], v[212:215], v[24:27]
	v_mfma_f32_16x16x32_bf16 v[12:15], v[132:135], v[220:223], v[12:15]
	v_mfma_f32_16x16x32_bf16 v[8:11], v[140:143], v[220:223], v[8:11]
	s_setprio 0
	s_setprio 1
	v_mfma_f32_16x16x32_bf16 v[52:55], v[144:147], v[178:181], 0
	v_mfma_f32_16x16x32_bf16 v[48:51], v[152:155], v[178:181], 0
	v_mfma_f32_16x16x32_bf16 v[36:39], v[144:147], v[200:203], 0
	v_mfma_f32_16x16x32_bf16 v[32:35], v[152:155], v[200:203], 0
	v_mfma_f32_16x16x32_bf16 v[20:23], v[144:147], v[208:211], 0
	v_mfma_f32_16x16x32_bf16 v[16:19], v[152:155], v[208:211], 0
	v_mfma_f32_16x16x32_bf16 v[4:7], v[144:147], v[216:219], 0
	v_mfma_f32_16x16x32_bf16 v[0:3], v[152:155], v[216:219], 0
	v_mfma_f32_16x16x32_bf16 v[52:55], v[148:151], v[196:199], v[52:55]
	v_mfma_f32_16x16x32_bf16 v[48:51], v[156:159], v[196:199], v[48:51]
	v_mfma_f32_16x16x32_bf16 v[36:39], v[148:151], v[204:207], v[36:39]
	v_mfma_f32_16x16x32_bf16 v[32:35], v[156:159], v[204:207], v[32:35]
	v_mfma_f32_16x16x32_bf16 v[20:23], v[148:151], v[212:215], v[20:23]
	v_mfma_f32_16x16x32_bf16 v[16:19], v[156:159], v[212:215], v[16:19]
	v_mfma_f32_16x16x32_bf16 v[4:7], v[148:151], v[220:223], v[4:7]
	v_mfma_f32_16x16x32_bf16 v[0:3], v[156:159], v[220:223], v[0:3]
	s_setprio 0
	s_barrier
	s_add_i32 s54, 0, 0x18000
	s_add_i32 s55, 0, 0x1c000
	v_add_u32_e32 v140, s54, v188
	v_add_u32_e32 v156, s55, v188
	ds_read_b128 v[128:131], v140
	ds_read_b128 v[132:135], v140 offset:1024
	ds_read_b128 v[136:139], v140 offset:2048
	ds_read_b128 v[140:143], v140 offset:3072
	ds_read_b128 v[144:147], v156
	ds_read_b128 v[148:151], v156 offset:1024
	ds_read_b128 v[152:155], v156 offset:2048
	ds_read_b128 v[156:159], v156 offset:3072
	s_add_u32 s28, s28, 0x40000
	s_addc_u32 s29, s29, 0
	s_mov_b32 m0, s36
	v_lshl_add_u64 v[232:233], s[28:29], 0, v[162:163]
	ds_read_b128 v[178:181], v195 offset:32768
	ds_read_b128 v[196:199], v195 offset:33792
	ds_read_b128 v[200:203], v195 offset:34816
	ds_read_b128 v[204:207], v195 offset:35840
	ds_read_b128 v[208:211], v195 offset:36864
	ds_read_b128 v[212:215], v195 offset:37888
	ds_read_b128 v[216:219], v195 offset:38912
	ds_read_b128 v[220:223], v195 offset:39936
	global_load_lds_dwordx4 v[232:233], off
	v_lshl_add_u64 v[232:233], s[28:29], 0, v[166:167]
	s_mov_b32 m0, s37
	s_nop 0
	global_load_lds_dwordx4 v[232:233], off
	s_waitcnt vmcnt(8)
	s_waitcnt lgkmcnt(0)
	s_barrier
	s_setprio 1
	s_waitcnt lgkmcnt(0)
	v_mfma_f32_16x16x32_bf16 v[124:127], v[128:131], v[178:181], v[124:127]
	v_mfma_f32_16x16x32_bf16 v[120:123], v[136:139], v[178:181], v[120:123]
	v_mfma_f32_16x16x32_bf16 v[108:111], v[128:131], v[200:203], v[108:111]
	v_mfma_f32_16x16x32_bf16 v[104:107], v[136:139], v[200:203], v[104:107]
	v_mfma_f32_16x16x32_bf16 v[92:95], v[128:131], v[208:211], v[92:95]
	v_mfma_f32_16x16x32_bf16 v[88:91], v[136:139], v[208:211], v[88:91]
	v_mfma_f32_16x16x32_bf16 v[76:79], v[128:131], v[216:219], v[76:79]
	v_mfma_f32_16x16x32_bf16 v[72:75], v[136:139], v[216:219], v[72:75]
	v_mfma_f32_16x16x32_bf16 v[124:127], v[132:135], v[196:199], v[124:127]
	v_mfma_f32_16x16x32_bf16 v[120:123], v[140:143], v[196:199], v[120:123]
	v_mfma_f32_16x16x32_bf16 v[108:111], v[132:135], v[204:207], v[108:111]
	v_mfma_f32_16x16x32_bf16 v[104:107], v[140:143], v[204:207], v[104:107]
	v_mfma_f32_16x16x32_bf16 v[92:95], v[132:135], v[212:215], v[92:95]
	v_mfma_f32_16x16x32_bf16 v[88:91], v[140:143], v[212:215], v[88:91]
	v_mfma_f32_16x16x32_bf16 v[76:79], v[132:135], v[220:223], v[76:79]
	v_mfma_f32_16x16x32_bf16 v[72:75], v[140:143], v[220:223], v[72:75]
	s_setprio 0
	s_setprio 1
	v_mfma_f32_16x16x32_bf16 v[116:119], v[144:147], v[178:181], v[116:119]
	v_mfma_f32_16x16x32_bf16 v[112:115], v[152:155], v[178:181], v[112:115]
	v_mfma_f32_16x16x32_bf16 v[100:103], v[144:147], v[200:203], v[100:103]
	v_mfma_f32_16x16x32_bf16 v[96:99], v[152:155], v[200:203], v[96:99]
	v_mfma_f32_16x16x32_bf16 v[84:87], v[144:147], v[208:211], v[84:87]
	v_mfma_f32_16x16x32_bf16 v[80:83], v[152:155], v[208:211], v[80:83]
	v_mfma_f32_16x16x32_bf16 v[68:71], v[144:147], v[216:219], v[68:71]
	v_mfma_f32_16x16x32_bf16 v[64:67], v[152:155], v[216:219], v[64:67]
	v_mfma_f32_16x16x32_bf16 v[116:119], v[148:151], v[196:199], v[116:119]
	v_mfma_f32_16x16x32_bf16 v[112:115], v[156:159], v[196:199], v[112:115]
	v_mfma_f32_16x16x32_bf16 v[100:103], v[148:151], v[204:207], v[100:103]
	v_mfma_f32_16x16x32_bf16 v[96:99], v[156:159], v[204:207], v[96:99]
	v_mfma_f32_16x16x32_bf16 v[84:87], v[148:151], v[212:215], v[84:87]
	v_mfma_f32_16x16x32_bf16 v[80:83], v[156:159], v[212:215], v[80:83]
	v_mfma_f32_16x16x32_bf16 v[68:71], v[148:151], v[220:223], v[68:71]
	v_mfma_f32_16x16x32_bf16 v[64:67], v[156:159], v[220:223], v[64:67]
	s_setprio 0
	s_barrier
	s_add_i32 s28, s54, s35
	v_lshl_add_u64 v[224:225], v[224:225], 0, s[10:11]
	s_mov_b32 m0, s28
	ds_read_b128 v[178:181], v195 offset:49152
	ds_read_b128 v[196:199], v195 offset:50176
	ds_read_b128 v[200:203], v195 offset:51200
	ds_read_b128 v[204:207], v195 offset:52224
	ds_read_b128 v[208:211], v195 offset:53248
	ds_read_b128 v[212:215], v195 offset:54272
	ds_read_b128 v[216:219], v195 offset:55296
	ds_read_b128 v[220:223], v195 offset:56320
	global_load_lds_dwordx4 v[224:225], off
	s_add_i32 m0, s28, 0x2000
	s_add_u32 s26, s26, 0x40080
	v_lshl_add_u64 v[224:225], v[226:227], 0, s[10:11]
	s_addc_u32 s27, s27, 0
	s_add_i32 s28, s55, s35
	global_load_lds_dwordx4 v[224:225], off
	v_lshl_add_u64 v[224:225], s[26:27], 0, v[164:165]
	s_mov_b32 m0, s28
	s_nop 0
	global_load_lds_dwordx4 v[224:225], off
	v_lshl_add_u64 v[224:225], s[26:27], 0, v[168:169]
	s_add_i32 m0, s28, 0x2000
	s_nop 0
	global_load_lds_dwordx4 v[224:225], off
	v_lshl_add_u64 v[224:225], v[228:229], 0, s[10:11]
	s_mov_b32 m0, s40
	s_nop 0
	global_load_lds_dwordx4 v[224:225], off
	v_lshl_add_u64 v[224:225], v[230:231], 0, s[10:11]
	s_mov_b32 m0, s41
	s_nop 0
	global_load_lds_dwordx4 v[224:225], off
	s_waitcnt vmcnt(8)
	s_waitcnt lgkmcnt(0)
	s_barrier
	s_setprio 1
	s_waitcnt lgkmcnt(0)
	v_mfma_f32_16x16x32_bf16 v[60:63], v[128:131], v[178:181], v[60:63]
	v_mfma_f32_16x16x32_bf16 v[56:59], v[136:139], v[178:181], v[56:59]
	v_mfma_f32_16x16x32_bf16 v[44:47], v[128:131], v[200:203], v[44:47]
	v_mfma_f32_16x16x32_bf16 v[40:43], v[136:139], v[200:203], v[40:43]
	v_mfma_f32_16x16x32_bf16 v[28:31], v[128:131], v[208:211], v[28:31]
	v_mfma_f32_16x16x32_bf16 v[24:27], v[136:139], v[208:211], v[24:27]
	v_mfma_f32_16x16x32_bf16 v[12:15], v[128:131], v[216:219], v[12:15]
	v_mfma_f32_16x16x32_bf16 v[8:11], v[136:139], v[216:219], v[8:11]
	v_mfma_f32_16x16x32_bf16 v[60:63], v[132:135], v[196:199], v[60:63]
	v_mfma_f32_16x16x32_bf16 v[56:59], v[140:143], v[196:199], v[56:59]
	v_mfma_f32_16x16x32_bf16 v[44:47], v[132:135], v[204:207], v[44:47]
	v_mfma_f32_16x16x32_bf16 v[40:43], v[140:143], v[204:207], v[40:43]
	v_mfma_f32_16x16x32_bf16 v[28:31], v[132:135], v[212:215], v[28:31]
	v_mfma_f32_16x16x32_bf16 v[24:27], v[140:143], v[212:215], v[24:27]
	v_mfma_f32_16x16x32_bf16 v[12:15], v[132:135], v[220:223], v[12:15]
	v_mfma_f32_16x16x32_bf16 v[8:11], v[140:143], v[220:223], v[8:11]
	s_setprio 0
	s_setprio 1
	v_mfma_f32_16x16x32_bf16 v[52:55], v[144:147], v[178:181], v[52:55]
	v_mfma_f32_16x16x32_bf16 v[48:51], v[152:155], v[178:181], v[48:51]
	v_mfma_f32_16x16x32_bf16 v[36:39], v[144:147], v[200:203], v[36:39]
	v_mfma_f32_16x16x32_bf16 v[32:35], v[152:155], v[200:203], v[32:35]
	v_mfma_f32_16x16x32_bf16 v[20:23], v[144:147], v[208:211], v[20:23]
	v_mfma_f32_16x16x32_bf16 v[16:19], v[152:155], v[208:211], v[16:19]
	v_mfma_f32_16x16x32_bf16 v[4:7], v[144:147], v[216:219], v[4:7]
	v_mfma_f32_16x16x32_bf16 v[0:3], v[152:155], v[216:219], v[0:3]
	v_mfma_f32_16x16x32_bf16 v[52:55], v[148:151], v[196:199], v[52:55]
	v_mfma_f32_16x16x32_bf16 v[48:51], v[156:159], v[196:199], v[48:51]
	v_mfma_f32_16x16x32_bf16 v[36:39], v[148:151], v[204:207], v[36:39]
	v_mfma_f32_16x16x32_bf16 v[32:35], v[156:159], v[204:207], v[32:35]
	v_mfma_f32_16x16x32_bf16 v[20:23], v[148:151], v[212:215], v[20:23]
	v_mfma_f32_16x16x32_bf16 v[16:19], v[156:159], v[212:215], v[16:19]
	v_mfma_f32_16x16x32_bf16 v[4:7], v[148:151], v[220:223], v[4:7]
	v_mfma_f32_16x16x32_bf16 v[0:3], v[156:159], v[220:223], v[0:3]
	s_setprio 0
	s_barrier
	s_add_i32 s53, s53, 2
	s_add_u32 s0, s0, 0x100
	s_addc_u32 s1, s1, 0
	s_add_u32 s51, s51, 0x100
	s_addc_u32 s52, s52, 0
	s_cmp_gt_u32 s53, 13
	s_cbranch_scc0 .LBB0_1403
	s_branch .Lpeel_exit_6

.LBB0_1487:
	s_ashr_i32 s15, s14, 31
	s_lshl_b64 s[16:17], s[14:15], 19
	s_add_u32 s16, s66, s16
	s_addc_u32 s17, s67, s17
	s_and_b64 s[18:19], s[4:5], exec
	s_cselect_b32 s15, s17, s1
	s_cselect_b32 s41, s16, s0
	s_ashr_i32 s13, s12, 31
	s_lshl_b64 s[18:19], s[12:13], 19
	s_add_u32 s18, s26, s18
	s_addc_u32 s19, s27, s19
	s_and_b64 s[24:25], s[4:5], exec
	s_cselect_b32 s13, s19, s23
	s_cselect_b32 s42, s18, s22
	s_add_u32 s0, s0, 0x40080
	s_addc_u32 s1, s1, 0
	s_add_u32 s43, s22, 0x100
	s_addc_u32 s44, s23, 0
	s_mov_b32 s45, -2
	ds_read_b128 v[144:147], v159
	ds_read_b128 v[148:151], v159 offset:1024
	ds_read_b128 v[152:155], v159 offset:2048
	ds_read_b128 v[166:169], v159 offset:3072
	ds_read_b128 v[170:173], v162
	ds_read_b128 v[174:177], v162 offset:1024
	ds_read_b128 v[178:181], v162 offset:2048
	ds_read_b128 v[188:191], v162 offset:3072
	s_add_u32 s22, s0, 0xfffc0080
	s_addc_u32 s23, s1, -1
	s_cmp_eq_u32 s45, 12
	s_cselect_b32 s25, s15, s23
	s_cselect_b32 s24, s41, s22
	s_cselect_b32 s23, s13, s44
	s_cselect_b32 s22, s42, s43
	v_lshl_add_u64 v[224:225], s[0:1], 0, v[136:137]
	s_add_i32 m0, s21, 0xc000
	ds_read_b128 v[192:195], v163
	ds_read_b128 v[196:199], v163 offset:1024
	ds_read_b128 v[200:203], v163 offset:2048
	ds_read_b128 v[204:207], v163 offset:3072
	ds_read_b128 v[208:211], v163 offset:4096
	ds_read_b128 v[212:215], v163 offset:5120
	ds_read_b128 v[216:219], v163 offset:6144
	ds_read_b128 v[220:223], v163 offset:7168
	global_load_lds_dwordx4 v[224:225], off
	v_lshl_add_u64 v[224:225], s[0:1], 0, v[138:139]
	s_add_i32 m0, s21, 0xe000
	s_nop 0
	global_load_lds_dwordx4 v[224:225], off
	s_waitcnt vmcnt(8)
	s_waitcnt lgkmcnt(0)
	s_barrier
	s_setprio 1
	s_waitcnt lgkmcnt(0)
	v_mfma_f32_16x16x32_bf16 v[124:127], v[144:147], v[192:195], 0
	v_mfma_f32_16x16x32_bf16 v[120:123], v[152:155], v[192:195], 0
	v_mfma_f32_16x16x32_bf16 v[116:119], v[144:147], v[200:203], 0
	v_mfma_f32_16x16x32_bf16 v[104:107], v[152:155], v[200:203], 0
	v_mfma_f32_16x16x32_bf16 v[92:95], v[144:147], v[208:211], 0
	v_mfma_f32_16x16x32_bf16 v[88:91], v[152:155], v[208:211], 0
	v_mfma_f32_16x16x32_bf16 v[76:79], v[144:147], v[216:219], 0
	v_mfma_f32_16x16x32_bf16 v[72:75], v[152:155], v[216:219], 0
	v_mfma_f32_16x16x32_bf16 v[124:127], v[148:151], v[196:199], v[124:127]
	v_mfma_f32_16x16x32_bf16 v[120:123], v[166:169], v[196:199], v[120:123]
	v_mfma_f32_16x16x32_bf16 v[116:119], v[148:151], v[204:207], v[116:119]
	v_mfma_f32_16x16x32_bf16 v[104:107], v[166:169], v[204:207], v[104:107]
	v_mfma_f32_16x16x32_bf16 v[92:95], v[148:151], v[212:215], v[92:95]
	v_mfma_f32_16x16x32_bf16 v[88:91], v[166:169], v[212:215], v[88:91]
	v_mfma_f32_16x16x32_bf16 v[76:79], v[148:151], v[220:223], v[76:79]
	v_mfma_f32_16x16x32_bf16 v[72:75], v[166:169], v[220:223], v[72:75]
	s_setprio 0
	s_setprio 1
	v_mfma_f32_16x16x32_bf16 v[112:115], v[170:173], v[192:195], 0
	v_mfma_f32_16x16x32_bf16 v[108:111], v[178:181], v[192:195], 0
	v_mfma_f32_16x16x32_bf16 v[100:103], v[170:173], v[200:203], 0
	v_mfma_f32_16x16x32_bf16 v[96:99], v[178:181], v[200:203], 0
	v_mfma_f32_16x16x32_bf16 v[84:87], v[170:173], v[208:211], 0
	v_mfma_f32_16x16x32_bf16 v[80:83], v[178:181], v[208:211], 0
	v_mfma_f32_16x16x32_bf16 v[68:71], v[170:173], v[216:219], 0
	v_mfma_f32_16x16x32_bf16 v[64:67], v[178:181], v[216:219], 0
	v_mfma_f32_16x16x32_bf16 v[112:115], v[174:177], v[196:199], v[112:115]
	v_mfma_f32_16x16x32_bf16 v[108:111], v[188:191], v[196:199], v[108:111]
	v_mfma_f32_16x16x32_bf16 v[100:103], v[174:177], v[204:207], v[100:103]
	v_mfma_f32_16x16x32_bf16 v[96:99], v[188:191], v[204:207], v[96:99]
	v_mfma_f32_16x16x32_bf16 v[84:87], v[174:177], v[212:215], v[84:87]
	v_mfma_f32_16x16x32_bf16 v[80:83], v[188:191], v[212:215], v[80:83]
	v_mfma_f32_16x16x32_bf16 v[68:71], v[174:177], v[220:223], v[68:71]
	v_mfma_f32_16x16x32_bf16 v[64:67], v[188:191], v[220:223], v[64:67]
	s_setprio 0
	s_barrier
	s_add_i32 s46, s39, s28
	v_lshl_add_u64 v[224:225], s[22:23], 0, v[132:133]
	s_mov_b32 m0, s46
	ds_read_b128 v[192:195], v163 offset:16384
	ds_read_b128 v[196:199], v163 offset:17408
	ds_read_b128 v[200:203], v163 offset:18432
	ds_read_b128 v[204:207], v163 offset:19456
	ds_read_b128 v[208:211], v163 offset:20480
	ds_read_b128 v[212:215], v163 offset:21504
	ds_read_b128 v[216:219], v163 offset:22528
	ds_read_b128 v[220:223], v163 offset:23552
	global_load_lds_dwordx4 v[224:225], off
	s_add_i32 m0, s46, 0x2000
	s_add_u32 s46, s22, 0x40000
	v_lshl_add_u64 v[226:227], s[22:23], 0, v[128:129]
	s_addc_u32 s47, s23, 0
	s_add_i32 s48, s40, s28
	global_load_lds_dwordx4 v[226:227], off
	v_lshl_add_u64 v[228:229], s[46:47], 0, v[132:133]
	s_mov_b32 m0, s48
	v_lshl_add_u64 v[230:231], s[24:25], 0, v[130:131]
	global_load_lds_dwordx4 v[228:229], off
	v_lshl_add_u64 v[228:229], s[46:47], 0, v[128:129]
	s_add_i32 m0, s48, 0x2000
	s_nop 0
	global_load_lds_dwordx4 v[228:229], off
	v_lshl_add_u64 v[228:229], s[24:25], 0, v[134:135]
	s_mov_b32 m0, s21
	s_nop 0
	global_load_lds_dwordx4 v[228:229], off
	s_mov_b32 m0, s31
	s_nop 0
	global_load_lds_dwordx4 v[230:231], off
	s_waitcnt vmcnt(8)
	s_waitcnt lgkmcnt(0)
	s_barrier
	s_setprio 1
	s_waitcnt lgkmcnt(0)
	v_mfma_f32_16x16x32_bf16 v[60:63], v[144:147], v[192:195], 0
	v_mfma_f32_16x16x32_bf16 v[56:59], v[152:155], v[192:195], 0
	v_mfma_f32_16x16x32_bf16 v[44:47], v[144:147], v[200:203], 0
	v_mfma_f32_16x16x32_bf16 v[40:43], v[152:155], v[200:203], 0
	v_mfma_f32_16x16x32_bf16 v[28:31], v[144:147], v[208:211], 0
	v_mfma_f32_16x16x32_bf16 v[24:27], v[152:155], v[208:211], 0
	v_mfma_f32_16x16x32_bf16 v[12:15], v[144:147], v[216:219], 0
	v_mfma_f32_16x16x32_bf16 v[8:11], v[152:155], v[216:219], 0
	v_mfma_f32_16x16x32_bf16 v[60:63], v[148:151], v[196:199], v[60:63]
	v_mfma_f32_16x16x32_bf16 v[56:59], v[166:169], v[196:199], v[56:59]
	v_mfma_f32_16x16x32_bf16 v[44:47], v[148:151], v[204:207], v[44:47]
	v_mfma_f32_16x16x32_bf16 v[40:43], v[166:169], v[204:207], v[40:43]
	v_mfma_f32_16x16x32_bf16 v[28:31], v[148:151], v[212:215], v[28:31]
	v_mfma_f32_16x16x32_bf16 v[24:27], v[166:169], v[212:215], v[24:27]
	v_mfma_f32_16x16x32_bf16 v[12:15], v[148:151], v[220:223], v[12:15]
	v_mfma_f32_16x16x32_bf16 v[8:11], v[166:169], v[220:223], v[8:11]
	s_setprio 0
	s_setprio 1
	v_mfma_f32_16x16x32_bf16 v[52:55], v[170:173], v[192:195], 0
	v_mfma_f32_16x16x32_bf16 v[48:51], v[178:181], v[192:195], 0
	v_mfma_f32_16x16x32_bf16 v[36:39], v[170:173], v[200:203], 0
	v_mfma_f32_16x16x32_bf16 v[32:35], v[178:181], v[200:203], 0
	v_mfma_f32_16x16x32_bf16 v[20:23], v[170:173], v[208:211], 0
	v_mfma_f32_16x16x32_bf16 v[16:19], v[178:181], v[208:211], 0
	v_mfma_f32_16x16x32_bf16 v[4:7], v[170:173], v[216:219], 0
	v_mfma_f32_16x16x32_bf16 v[0:3], v[178:181], v[216:219], 0
	v_mfma_f32_16x16x32_bf16 v[52:55], v[174:177], v[196:199], v[52:55]
	v_mfma_f32_16x16x32_bf16 v[48:51], v[188:191], v[196:199], v[48:51]
	v_mfma_f32_16x16x32_bf16 v[36:39], v[174:177], v[204:207], v[36:39]
	v_mfma_f32_16x16x32_bf16 v[32:35], v[188:191], v[204:207], v[32:35]
	v_mfma_f32_16x16x32_bf16 v[20:23], v[174:177], v[212:215], v[20:23]
	v_mfma_f32_16x16x32_bf16 v[16:19], v[188:191], v[212:215], v[16:19]
	v_mfma_f32_16x16x32_bf16 v[4:7], v[174:177], v[220:223], v[4:7]
	v_mfma_f32_16x16x32_bf16 v[0:3], v[188:191], v[220:223], v[0:3]
	s_setprio 0
	s_barrier
	s_add_i32 s46, 0, 0x18000
	v_add_u32_e32 v165, s46, v157
	s_add_i32 s47, 0, 0x1c000
	ds_read_b128 v[144:147], v165
	ds_read_b128 v[148:151], v165 offset:1024
	ds_read_b128 v[152:155], v165 offset:2048
	ds_read_b128 v[166:169], v165 offset:3072
	v_add_u32_e32 v165, s47, v157
	ds_read_b128 v[170:173], v165
	ds_read_b128 v[174:177], v165 offset:1024
	ds_read_b128 v[178:181], v165 offset:2048
	ds_read_b128 v[188:191], v165 offset:3072
	s_add_u32 s24, s24, 0x40000
	s_addc_u32 s25, s25, 0
	s_mov_b32 m0, s34
	v_lshl_add_u64 v[232:233], s[24:25], 0, v[134:135]
	ds_read_b128 v[192:195], v163 offset:32768
	ds_read_b128 v[196:199], v163 offset:33792
	ds_read_b128 v[200:203], v163 offset:34816
	ds_read_b128 v[204:207], v163 offset:35840
	ds_read_b128 v[208:211], v163 offset:36864
	ds_read_b128 v[212:215], v163 offset:37888
	ds_read_b128 v[216:219], v163 offset:38912
	ds_read_b128 v[220:223], v163 offset:39936
	global_load_lds_dwordx4 v[232:233], off
	v_lshl_add_u64 v[232:233], s[24:25], 0, v[130:131]
	s_mov_b32 m0, s35
	s_nop 0
	global_load_lds_dwordx4 v[232:233], off
	s_waitcnt vmcnt(8)
	s_waitcnt lgkmcnt(0)
	s_barrier
	s_setprio 1
	s_waitcnt lgkmcnt(0)
	v_mfma_f32_16x16x32_bf16 v[124:127], v[144:147], v[192:195], v[124:127]
	v_mfma_f32_16x16x32_bf16 v[120:123], v[152:155], v[192:195], v[120:123]
	v_mfma_f32_16x16x32_bf16 v[116:119], v[144:147], v[200:203], v[116:119]
	v_mfma_f32_16x16x32_bf16 v[104:107], v[152:155], v[200:203], v[104:107]
	v_mfma_f32_16x16x32_bf16 v[92:95], v[144:147], v[208:211], v[92:95]
	v_mfma_f32_16x16x32_bf16 v[88:91], v[152:155], v[208:211], v[88:91]
	v_mfma_f32_16x16x32_bf16 v[76:79], v[144:147], v[216:219], v[76:79]
	v_mfma_f32_16x16x32_bf16 v[72:75], v[152:155], v[216:219], v[72:75]
	v_mfma_f32_16x16x32_bf16 v[124:127], v[148:151], v[196:199], v[124:127]
	v_mfma_f32_16x16x32_bf16 v[120:123], v[166:169], v[196:199], v[120:123]
	v_mfma_f32_16x16x32_bf16 v[116:119], v[148:151], v[204:207], v[116:119]
	v_mfma_f32_16x16x32_bf16 v[104:107], v[166:169], v[204:207], v[104:107]
	v_mfma_f32_16x16x32_bf16 v[92:95], v[148:151], v[212:215], v[92:95]
	v_mfma_f32_16x16x32_bf16 v[88:91], v[166:169], v[212:215], v[88:91]
	v_mfma_f32_16x16x32_bf16 v[76:79], v[148:151], v[220:223], v[76:79]
	v_mfma_f32_16x16x32_bf16 v[72:75], v[166:169], v[220:223], v[72:75]
	s_setprio 0
	s_setprio 1
	v_mfma_f32_16x16x32_bf16 v[112:115], v[170:173], v[192:195], v[112:115]
	v_mfma_f32_16x16x32_bf16 v[108:111], v[178:181], v[192:195], v[108:111]
	v_mfma_f32_16x16x32_bf16 v[100:103], v[170:173], v[200:203], v[100:103]
	v_mfma_f32_16x16x32_bf16 v[96:99], v[178:181], v[200:203], v[96:99]
	v_mfma_f32_16x16x32_bf16 v[84:87], v[170:173], v[208:211], v[84:87]
	v_mfma_f32_16x16x32_bf16 v[80:83], v[178:181], v[208:211], v[80:83]
	v_mfma_f32_16x16x32_bf16 v[68:71], v[170:173], v[216:219], v[68:71]
	v_mfma_f32_16x16x32_bf16 v[64:67], v[178:181], v[216:219], v[64:67]
	v_mfma_f32_16x16x32_bf16 v[112:115], v[174:177], v[196:199], v[112:115]
	v_mfma_f32_16x16x32_bf16 v[108:111], v[188:191], v[196:199], v[108:111]
	v_mfma_f32_16x16x32_bf16 v[100:103], v[174:177], v[204:207], v[100:103]
	v_mfma_f32_16x16x32_bf16 v[96:99], v[188:191], v[204:207], v[96:99]
	v_mfma_f32_16x16x32_bf16 v[84:87], v[174:177], v[212:215], v[84:87]
	v_mfma_f32_16x16x32_bf16 v[80:83], v[188:191], v[212:215], v[80:83]
	v_mfma_f32_16x16x32_bf16 v[68:71], v[174:177], v[220:223], v[68:71]
	v_mfma_f32_16x16x32_bf16 v[64:67], v[188:191], v[220:223], v[64:67]
	s_setprio 0
	s_barrier
	s_add_i32 s24, s46, s28
	v_lshl_add_u64 v[224:225], v[224:225], 0, s[6:7]
	s_mov_b32 m0, s24
	ds_read_b128 v[192:195], v163 offset:49152
	ds_read_b128 v[196:199], v163 offset:50176
	ds_read_b128 v[200:203], v163 offset:51200
	ds_read_b128 v[204:207], v163 offset:52224
	ds_read_b128 v[208:211], v163 offset:53248
	ds_read_b128 v[212:215], v163 offset:54272
	ds_read_b128 v[216:219], v163 offset:55296
	ds_read_b128 v[220:223], v163 offset:56320
	global_load_lds_dwordx4 v[224:225], off
	s_add_i32 m0, s24, 0x2000
	s_add_u32 s22, s22, 0x40080
	v_lshl_add_u64 v[224:225], v[226:227], 0, s[6:7]
	s_addc_u32 s23, s23, 0
	s_add_i32 s24, s47, s28
	global_load_lds_dwordx4 v[224:225], off
	v_lshl_add_u64 v[224:225], s[22:23], 0, v[132:133]
	s_mov_b32 m0, s24
	s_nop 0
	global_load_lds_dwordx4 v[224:225], off
	v_lshl_add_u64 v[224:225], s[22:23], 0, v[128:129]
	s_add_i32 m0, s24, 0x2000
	s_nop 0
	global_load_lds_dwordx4 v[224:225], off
	v_lshl_add_u64 v[224:225], v[228:229], 0, s[6:7]
	s_mov_b32 m0, s37
	s_nop 0
	global_load_lds_dwordx4 v[224:225], off
	v_lshl_add_u64 v[224:225], v[230:231], 0, s[6:7]
	s_mov_b32 m0, s38
	s_nop 0
	global_load_lds_dwordx4 v[224:225], off
	s_waitcnt vmcnt(8)
	s_waitcnt lgkmcnt(0)
	s_barrier
	s_setprio 1
	s_waitcnt lgkmcnt(0)
	v_mfma_f32_16x16x32_bf16 v[60:63], v[144:147], v[192:195], v[60:63]
	v_mfma_f32_16x16x32_bf16 v[56:59], v[152:155], v[192:195], v[56:59]
	v_mfma_f32_16x16x32_bf16 v[44:47], v[144:147], v[200:203], v[44:47]
	v_mfma_f32_16x16x32_bf16 v[40:43], v[152:155], v[200:203], v[40:43]
	v_mfma_f32_16x16x32_bf16 v[28:31], v[144:147], v[208:211], v[28:31]
	v_mfma_f32_16x16x32_bf16 v[24:27], v[152:155], v[208:211], v[24:27]
	v_mfma_f32_16x16x32_bf16 v[12:15], v[144:147], v[216:219], v[12:15]
	v_mfma_f32_16x16x32_bf16 v[8:11], v[152:155], v[216:219], v[8:11]
	v_mfma_f32_16x16x32_bf16 v[60:63], v[148:151], v[196:199], v[60:63]
	v_mfma_f32_16x16x32_bf16 v[56:59], v[166:169], v[196:199], v[56:59]
	v_mfma_f32_16x16x32_bf16 v[44:47], v[148:151], v[204:207], v[44:47]
	v_mfma_f32_16x16x32_bf16 v[40:43], v[166:169], v[204:207], v[40:43]
	v_mfma_f32_16x16x32_bf16 v[28:31], v[148:151], v[212:215], v[28:31]
	v_mfma_f32_16x16x32_bf16 v[24:27], v[166:169], v[212:215], v[24:27]
	v_mfma_f32_16x16x32_bf16 v[12:15], v[148:151], v[220:223], v[12:15]
	v_mfma_f32_16x16x32_bf16 v[8:11], v[166:169], v[220:223], v[8:11]
	s_setprio 0
	s_setprio 1
	v_mfma_f32_16x16x32_bf16 v[52:55], v[170:173], v[192:195], v[52:55]
	v_mfma_f32_16x16x32_bf16 v[48:51], v[178:181], v[192:195], v[48:51]
	v_mfma_f32_16x16x32_bf16 v[36:39], v[170:173], v[200:203], v[36:39]
	v_mfma_f32_16x16x32_bf16 v[32:35], v[178:181], v[200:203], v[32:35]
	v_mfma_f32_16x16x32_bf16 v[20:23], v[170:173], v[208:211], v[20:23]
	v_mfma_f32_16x16x32_bf16 v[16:19], v[178:181], v[208:211], v[16:19]
	v_mfma_f32_16x16x32_bf16 v[4:7], v[170:173], v[216:219], v[4:7]
	v_mfma_f32_16x16x32_bf16 v[0:3], v[178:181], v[216:219], v[0:3]
	v_mfma_f32_16x16x32_bf16 v[52:55], v[174:177], v[196:199], v[52:55]
	v_mfma_f32_16x16x32_bf16 v[48:51], v[188:191], v[196:199], v[48:51]
	v_mfma_f32_16x16x32_bf16 v[36:39], v[174:177], v[204:207], v[36:39]
	v_mfma_f32_16x16x32_bf16 v[32:35], v[188:191], v[204:207], v[32:35]
	v_mfma_f32_16x16x32_bf16 v[20:23], v[174:177], v[212:215], v[20:23]
	v_mfma_f32_16x16x32_bf16 v[16:19], v[188:191], v[212:215], v[16:19]
	v_mfma_f32_16x16x32_bf16 v[4:7], v[174:177], v[220:223], v[4:7]
	v_mfma_f32_16x16x32_bf16 v[0:3], v[188:191], v[220:223], v[0:3]
	s_setprio 0
	s_barrier
	s_add_i32 s45, s45, 2
	s_add_u32 s0, s0, 0x100
	s_addc_u32 s1, s1, 0
	s_add_u32 s43, s43, 0x100
	s_addc_u32 s44, s44, 0
	s_cmp_gt_u32 s45, 13
	s_cbranch_scc0 .LBB0_1488
	s_branch .Lpeel_exit_7

.Lpeel_exit_7:
	s_and_b64 vcc, exec, s[10:11]
	s_cbranch_vccz .LBB0_1491
	s_barrier

.LBB0_1562:
	s_ashr_i32 s17, s16, 31
	s_lshl_b64 s[18:19], s[16:17], 21
	s_add_u32 s18, s68, s18
	s_addc_u32 s19, s69, s19
	s_and_b64 s[20:21], s[4:5], exec
	s_cselect_b32 s17, s19, s1
	s_cselect_b32 s33, s18, s0
	s_ashr_i32 s15, s14, 31
	s_lshl_b64 s[20:21], s[14:15], 21
	s_add_u32 s20, s30, s20
	s_addc_u32 s21, s31, s21
	s_and_b64 s[28:29], s[4:5], exec
	s_cselect_b32 s15, s21, s27
	s_cselect_b32 s49, s20, s26
	s_add_u32 s0, s0, 0x100080
	s_addc_u32 s1, s1, 0
	s_add_u32 s50, s26, 0x100
	s_addc_u32 s51, s27, 0
	s_mov_b32 s52, -2
	s_waitcnt lgkmcnt(0)
	ds_read_b128 v[128:131], v193
	ds_read_b128 v[132:135], v193 offset:1024
	ds_read_b128 v[136:139], v193 offset:2048
	ds_read_b128 v[140:143], v193 offset:3072
	ds_read_b128 v[144:147], v194
	ds_read_b128 v[148:151], v194 offset:1024
	ds_read_b128 v[152:155], v194 offset:2048
	ds_read_b128 v[156:159], v194 offset:3072
	s_add_u32 s26, s0, 0xfff00080
	s_addc_u32 s27, s1, -1
	s_cmp_eq_u32 s52, 60
	s_cselect_b32 s29, s17, s27
	s_cselect_b32 s28, s33, s26
	s_cselect_b32 s27, s15, s51
	s_cselect_b32 s26, s49, s50
	v_lshl_add_u64 v[224:225], s[0:1], 0, v[170:171]
	s_add_i32 m0, s23, 0xc000
	ds_read_b128 v[178:181], v195
	ds_read_b128 v[196:199], v195 offset:1024
	ds_read_b128 v[200:203], v195 offset:2048
	ds_read_b128 v[204:207], v195 offset:3072
	ds_read_b128 v[208:211], v195 offset:4096
	ds_read_b128 v[212:215], v195 offset:5120
	ds_read_b128 v[216:219], v195 offset:6144
	ds_read_b128 v[220:223], v195 offset:7168
	global_load_lds_dwordx4 v[224:225], off
	v_lshl_add_u64 v[224:225], s[0:1], 0, v[172:173]
	s_add_i32 m0, s23, 0xe000
	s_nop 0
	global_load_lds_dwordx4 v[224:225], off
	s_waitcnt vmcnt(8)
	s_waitcnt lgkmcnt(0)
	s_barrier
	s_setprio 1
	s_waitcnt lgkmcnt(0)
	v_mfma_f32_16x16x32_bf16 v[124:127], v[128:131], v[178:181], 0
	v_mfma_f32_16x16x32_bf16 v[120:123], v[136:139], v[178:181], 0
	v_mfma_f32_16x16x32_bf16 v[108:111], v[128:131], v[200:203], 0
	v_mfma_f32_16x16x32_bf16 v[104:107], v[136:139], v[200:203], 0
	v_mfma_f32_16x16x32_bf16 v[92:95], v[128:131], v[208:211], 0
	v_mfma_f32_16x16x32_bf16 v[88:91], v[136:139], v[208:211], 0
	v_mfma_f32_16x16x32_bf16 v[76:79], v[128:131], v[216:219], 0
	v_mfma_f32_16x16x32_bf16 v[72:75], v[136:139], v[216:219], 0
	v_mfma_f32_16x16x32_bf16 v[124:127], v[132:135], v[196:199], v[124:127]
	v_mfma_f32_16x16x32_bf16 v[120:123], v[140:143], v[196:199], v[120:123]
	v_mfma_f32_16x16x32_bf16 v[108:111], v[132:135], v[204:207], v[108:111]
	v_mfma_f32_16x16x32_bf16 v[104:107], v[140:143], v[204:207], v[104:107]
	v_mfma_f32_16x16x32_bf16 v[92:95], v[132:135], v[212:215], v[92:95]
	v_mfma_f32_16x16x32_bf16 v[88:91], v[140:143], v[212:215], v[88:91]
	v_mfma_f32_16x16x32_bf16 v[76:79], v[132:135], v[220:223], v[76:79]
	v_mfma_f32_16x16x32_bf16 v[72:75], v[140:143], v[220:223], v[72:75]
	s_setprio 0
	s_setprio 1
	v_mfma_f32_16x16x32_bf16 v[116:119], v[144:147], v[178:181], 0
	v_mfma_f32_16x16x32_bf16 v[112:115], v[152:155], v[178:181], 0
	v_mfma_f32_16x16x32_bf16 v[100:103], v[144:147], v[200:203], 0
	v_mfma_f32_16x16x32_bf16 v[96:99], v[152:155], v[200:203], 0
	v_mfma_f32_16x16x32_bf16 v[84:87], v[144:147], v[208:211], 0
	v_mfma_f32_16x16x32_bf16 v[80:83], v[152:155], v[208:211], 0
	v_mfma_f32_16x16x32_bf16 v[68:71], v[144:147], v[216:219], 0
	v_mfma_f32_16x16x32_bf16 v[64:67], v[152:155], v[216:219], 0
	v_mfma_f32_16x16x32_bf16 v[116:119], v[148:151], v[196:199], v[116:119]
	v_mfma_f32_16x16x32_bf16 v[112:115], v[156:159], v[196:199], v[112:115]
	v_mfma_f32_16x16x32_bf16 v[100:103], v[148:151], v[204:207], v[100:103]
	v_mfma_f32_16x16x32_bf16 v[96:99], v[156:159], v[204:207], v[96:99]
	v_mfma_f32_16x16x32_bf16 v[84:87], v[148:151], v[212:215], v[84:87]
	v_mfma_f32_16x16x32_bf16 v[80:83], v[156:159], v[212:215], v[80:83]
	v_mfma_f32_16x16x32_bf16 v[68:71], v[148:151], v[220:223], v[68:71]
	v_mfma_f32_16x16x32_bf16 v[64:67], v[156:159], v[220:223], v[64:67]
	s_setprio 0
	s_barrier
	s_add_i32 s53, s43, s34
	v_lshl_add_u64 v[224:225], s[26:27], 0, v[164:165]
	s_mov_b32 m0, s53
	ds_read_b128 v[178:181], v195 offset:16384
	ds_read_b128 v[196:199], v195 offset:17408
	ds_read_b128 v[200:203], v195 offset:18432
	ds_read_b128 v[204:207], v195 offset:19456
	ds_read_b128 v[208:211], v195 offset:20480
	ds_read_b128 v[212:215], v195 offset:21504
	ds_read_b128 v[216:219], v195 offset:22528
	ds_read_b128 v[220:223], v195 offset:23552
	global_load_lds_dwordx4 v[224:225], off
	s_add_i32 m0, s53, 0x2000
	s_add_u32 s54, s26, 0x100000
	v_lshl_add_u64 v[226:227], s[26:27], 0, v[168:169]
	s_addc_u32 s55, s27, 0
	s_add_i32 s53, s44, s34
	global_load_lds_dwordx4 v[226:227], off
	v_lshl_add_u64 v[228:229], s[54:55], 0, v[164:165]
	s_mov_b32 m0, s53
	v_lshl_add_u64 v[230:231], s[28:29], 0, v[166:167]
	global_load_lds_dwordx4 v[228:229], off
	v_lshl_add_u64 v[228:229], s[54:55], 0, v[168:169]
	s_add_i32 m0, s53, 0x2000
	s_nop 0
	global_load_lds_dwordx4 v[228:229], off
	v_lshl_add_u64 v[228:229], s[28:29], 0, v[162:163]
	s_mov_b32 m0, s23
	s_nop 0
	global_load_lds_dwordx4 v[228:229], off
	s_mov_b32 m0, s25
	s_nop 0
	global_load_lds_dwordx4 v[230:231], off
	s_waitcnt vmcnt(8)
	s_waitcnt lgkmcnt(0)
	s_barrier
	s_setprio 1
	s_waitcnt lgkmcnt(0)
	v_mfma_f32_16x16x32_bf16 v[60:63], v[128:131], v[178:181], 0
	v_mfma_f32_16x16x32_bf16 v[56:59], v[136:139], v[178:181], 0
	v_mfma_f32_16x16x32_bf16 v[44:47], v[128:131], v[200:203], 0
	v_mfma_f32_16x16x32_bf16 v[40:43], v[136:139], v[200:203], 0
	v_mfma_f32_16x16x32_bf16 v[28:31], v[128:131], v[208:211], 0
	v_mfma_f32_16x16x32_bf16 v[24:27], v[136:139], v[208:211], 0
	v_mfma_f32_16x16x32_bf16 v[12:15], v[128:131], v[216:219], 0
	v_mfma_f32_16x16x32_bf16 v[8:11], v[136:139], v[216:219], 0
	v_mfma_f32_16x16x32_bf16 v[60:63], v[132:135], v[196:199], v[60:63]
	v_mfma_f32_16x16x32_bf16 v[56:59], v[140:143], v[196:199], v[56:59]
	v_mfma_f32_16x16x32_bf16 v[44:47], v[132:135], v[204:207], v[44:47]
	v_mfma_f32_16x16x32_bf16 v[40:43], v[140:143], v[204:207], v[40:43]
	v_mfma_f32_16x16x32_bf16 v[28:31], v[132:135], v[212:215], v[28:31]
	v_mfma_f32_16x16x32_bf16 v[24:27], v[140:143], v[212:215], v[24:27]
	v_mfma_f32_16x16x32_bf16 v[12:15], v[132:135], v[220:223], v[12:15]
	v_mfma_f32_16x16x32_bf16 v[8:11], v[140:143], v[220:223], v[8:11]
	s_setprio 0
	s_setprio 1
	v_mfma_f32_16x16x32_bf16 v[52:55], v[144:147], v[178:181], 0
	v_mfma_f32_16x16x32_bf16 v[48:51], v[152:155], v[178:181], 0
	v_mfma_f32_16x16x32_bf16 v[36:39], v[144:147], v[200:203], 0
	v_mfma_f32_16x16x32_bf16 v[32:35], v[152:155], v[200:203], 0
	v_mfma_f32_16x16x32_bf16 v[20:23], v[144:147], v[208:211], 0
	v_mfma_f32_16x16x32_bf16 v[16:19], v[152:155], v[208:211], 0
	v_mfma_f32_16x16x32_bf16 v[4:7], v[144:147], v[216:219], 0
	v_mfma_f32_16x16x32_bf16 v[0:3], v[152:155], v[216:219], 0
	v_mfma_f32_16x16x32_bf16 v[52:55], v[148:151], v[196:199], v[52:55]
	v_mfma_f32_16x16x32_bf16 v[48:51], v[156:159], v[196:199], v[48:51]
	v_mfma_f32_16x16x32_bf16 v[36:39], v[148:151], v[204:207], v[36:39]
	v_mfma_f32_16x16x32_bf16 v[32:35], v[156:159], v[204:207], v[32:35]
	v_mfma_f32_16x16x32_bf16 v[20:23], v[148:151], v[212:215], v[20:23]
	v_mfma_f32_16x16x32_bf16 v[16:19], v[156:159], v[212:215], v[16:19]
	v_mfma_f32_16x16x32_bf16 v[4:7], v[148:151], v[220:223], v[4:7]
	v_mfma_f32_16x16x32_bf16 v[0:3], v[156:159], v[220:223], v[0:3]
	s_setprio 0
	s_barrier
	s_add_i32 s53, 0, 0x18000
	s_add_i32 s54, 0, 0x1c000
	v_add_u32_e32 v140, s53, v188
	v_add_u32_e32 v156, s54, v188
	ds_read_b128 v[128:131], v140
	ds_read_b128 v[132:135], v140 offset:1024
	ds_read_b128 v[136:139], v140 offset:2048
	ds_read_b128 v[140:143], v140 offset:3072
	ds_read_b128 v[144:147], v156
	ds_read_b128 v[148:151], v156 offset:1024
	ds_read_b128 v[152:155], v156 offset:2048
	ds_read_b128 v[156:159], v156 offset:3072
	s_add_u32 s28, s28, 0x100000
	s_addc_u32 s29, s29, 0
	s_mov_b32 m0, s35
	v_lshl_add_u64 v[232:233], s[28:29], 0, v[162:163]
	ds_read_b128 v[178:181], v195 offset:32768
	ds_read_b128 v[196:199], v195 offset:33792
	ds_read_b128 v[200:203], v195 offset:34816
	ds_read_b128 v[204:207], v195 offset:35840
	ds_read_b128 v[208:211], v195 offset:36864
	ds_read_b128 v[212:215], v195 offset:37888
	ds_read_b128 v[216:219], v195 offset:38912
	ds_read_b128 v[220:223], v195 offset:39936
	global_load_lds_dwordx4 v[232:233], off
	v_lshl_add_u64 v[232:233], s[28:29], 0, v[166:167]
	s_mov_b32 m0, s36
	s_nop 0
	global_load_lds_dwordx4 v[232:233], off
	s_waitcnt vmcnt(8)
	s_waitcnt lgkmcnt(0)
	s_barrier
	s_setprio 1
	s_waitcnt lgkmcnt(0)
	v_mfma_f32_16x16x32_bf16 v[124:127], v[128:131], v[178:181], v[124:127]
	v_mfma_f32_16x16x32_bf16 v[120:123], v[136:139], v[178:181], v[120:123]
	v_mfma_f32_16x16x32_bf16 v[108:111], v[128:131], v[200:203], v[108:111]
	v_mfma_f32_16x16x32_bf16 v[104:107], v[136:139], v[200:203], v[104:107]
	v_mfma_f32_16x16x32_bf16 v[92:95], v[128:131], v[208:211], v[92:95]
	v_mfma_f32_16x16x32_bf16 v[88:91], v[136:139], v[208:211], v[88:91]
	v_mfma_f32_16x16x32_bf16 v[76:79], v[128:131], v[216:219], v[76:79]
	v_mfma_f32_16x16x32_bf16 v[72:75], v[136:139], v[216:219], v[72:75]
	v_mfma_f32_16x16x32_bf16 v[124:127], v[132:135], v[196:199], v[124:127]
	v_mfma_f32_16x16x32_bf16 v[120:123], v[140:143], v[196:199], v[120:123]
	v_mfma_f32_16x16x32_bf16 v[108:111], v[132:135], v[204:207], v[108:111]
	v_mfma_f32_16x16x32_bf16 v[104:107], v[140:143], v[204:207], v[104:107]
	v_mfma_f32_16x16x32_bf16 v[92:95], v[132:135], v[212:215], v[92:95]
	v_mfma_f32_16x16x32_bf16 v[88:91], v[140:143], v[212:215], v[88:91]
	v_mfma_f32_16x16x32_bf16 v[76:79], v[132:135], v[220:223], v[76:79]
	v_mfma_f32_16x16x32_bf16 v[72:75], v[140:143], v[220:223], v[72:75]
	s_setprio 0
	s_setprio 1
	v_mfma_f32_16x16x32_bf16 v[116:119], v[144:147], v[178:181], v[116:119]
	v_mfma_f32_16x16x32_bf16 v[112:115], v[152:155], v[178:181], v[112:115]
	v_mfma_f32_16x16x32_bf16 v[100:103], v[144:147], v[200:203], v[100:103]
	v_mfma_f32_16x16x32_bf16 v[96:99], v[152:155], v[200:203], v[96:99]
	v_mfma_f32_16x16x32_bf16 v[84:87], v[144:147], v[208:211], v[84:87]
	v_mfma_f32_16x16x32_bf16 v[80:83], v[152:155], v[208:211], v[80:83]
	v_mfma_f32_16x16x32_bf16 v[68:71], v[144:147], v[216:219], v[68:71]
	v_mfma_f32_16x16x32_bf16 v[64:67], v[152:155], v[216:219], v[64:67]
	v_mfma_f32_16x16x32_bf16 v[116:119], v[148:151], v[196:199], v[116:119]
	v_mfma_f32_16x16x32_bf16 v[112:115], v[156:159], v[196:199], v[112:115]
	v_mfma_f32_16x16x32_bf16 v[100:103], v[148:151], v[204:207], v[100:103]
	v_mfma_f32_16x16x32_bf16 v[96:99], v[156:159], v[204:207], v[96:99]
	v_mfma_f32_16x16x32_bf16 v[84:87], v[148:151], v[212:215], v[84:87]
	v_mfma_f32_16x16x32_bf16 v[80:83], v[156:159], v[212:215], v[80:83]
	v_mfma_f32_16x16x32_bf16 v[68:71], v[148:151], v[220:223], v[68:71]
	v_mfma_f32_16x16x32_bf16 v[64:67], v[156:159], v[220:223], v[64:67]
	s_setprio 0
	s_barrier
	s_add_i32 s28, s53, s34
	v_lshl_add_u64 v[224:225], v[224:225], 0, s[10:11]
	s_mov_b32 m0, s28
	ds_read_b128 v[178:181], v195 offset:49152
	ds_read_b128 v[196:199], v195 offset:50176
	ds_read_b128 v[200:203], v195 offset:51200
	ds_read_b128 v[204:207], v195 offset:52224
	ds_read_b128 v[208:211], v195 offset:53248
	ds_read_b128 v[212:215], v195 offset:54272
	ds_read_b128 v[216:219], v195 offset:55296
	ds_read_b128 v[220:223], v195 offset:56320
	global_load_lds_dwordx4 v[224:225], off
	s_add_i32 m0, s28, 0x2000
	s_add_u32 s26, s26, 0x100080
	v_lshl_add_u64 v[224:225], v[226:227], 0, s[10:11]
	s_addc_u32 s27, s27, 0
	s_add_i32 s28, s54, s34
	global_load_lds_dwordx4 v[224:225], off
	v_lshl_add_u64 v[224:225], s[26:27], 0, v[164:165]
	s_mov_b32 m0, s28
	s_nop 0
	global_load_lds_dwordx4 v[224:225], off
	v_lshl_add_u64 v[224:225], s[26:27], 0, v[168:169]
	s_add_i32 m0, s28, 0x2000
	s_nop 0
	global_load_lds_dwordx4 v[224:225], off
	v_lshl_add_u64 v[224:225], v[228:229], 0, s[10:11]
	s_mov_b32 m0, s39
	s_nop 0
	global_load_lds_dwordx4 v[224:225], off
	v_lshl_add_u64 v[224:225], v[230:231], 0, s[10:11]
	s_mov_b32 m0, s40
	s_nop 0
	global_load_lds_dwordx4 v[224:225], off
	s_waitcnt vmcnt(8)
	s_waitcnt lgkmcnt(0)
	s_barrier
	s_setprio 1
	s_waitcnt lgkmcnt(0)
	v_mfma_f32_16x16x32_bf16 v[60:63], v[128:131], v[178:181], v[60:63]
	v_mfma_f32_16x16x32_bf16 v[56:59], v[136:139], v[178:181], v[56:59]
	v_mfma_f32_16x16x32_bf16 v[44:47], v[128:131], v[200:203], v[44:47]
	v_mfma_f32_16x16x32_bf16 v[40:43], v[136:139], v[200:203], v[40:43]
	v_mfma_f32_16x16x32_bf16 v[28:31], v[128:131], v[208:211], v[28:31]
	v_mfma_f32_16x16x32_bf16 v[24:27], v[136:139], v[208:211], v[24:27]
	v_mfma_f32_16x16x32_bf16 v[12:15], v[128:131], v[216:219], v[12:15]
	v_mfma_f32_16x16x32_bf16 v[8:11], v[136:139], v[216:219], v[8:11]
	v_mfma_f32_16x16x32_bf16 v[60:63], v[132:135], v[196:199], v[60:63]
	v_mfma_f32_16x16x32_bf16 v[56:59], v[140:143], v[196:199], v[56:59]
	v_mfma_f32_16x16x32_bf16 v[44:47], v[132:135], v[204:207], v[44:47]
	v_mfma_f32_16x16x32_bf16 v[40:43], v[140:143], v[204:207], v[40:43]
	v_mfma_f32_16x16x32_bf16 v[28:31], v[132:135], v[212:215], v[28:31]
	v_mfma_f32_16x16x32_bf16 v[24:27], v[140:143], v[212:215], v[24:27]
	v_mfma_f32_16x16x32_bf16 v[12:15], v[132:135], v[220:223], v[12:15]
	v_mfma_f32_16x16x32_bf16 v[8:11], v[140:143], v[220:223], v[8:11]
	s_setprio 0
	s_setprio 1
	v_mfma_f32_16x16x32_bf16 v[52:55], v[144:147], v[178:181], v[52:55]
	v_mfma_f32_16x16x32_bf16 v[48:51], v[152:155], v[178:181], v[48:51]
	v_mfma_f32_16x16x32_bf16 v[36:39], v[144:147], v[200:203], v[36:39]
	v_mfma_f32_16x16x32_bf16 v[32:35], v[152:155], v[200:203], v[32:35]
	v_mfma_f32_16x16x32_bf16 v[20:23], v[144:147], v[208:211], v[20:23]
	v_mfma_f32_16x16x32_bf16 v[16:19], v[152:155], v[208:211], v[16:19]
	v_mfma_f32_16x16x32_bf16 v[4:7], v[144:147], v[216:219], v[4:7]
	v_mfma_f32_16x16x32_bf16 v[0:3], v[152:155], v[216:219], v[0:3]
	v_mfma_f32_16x16x32_bf16 v[52:55], v[148:151], v[196:199], v[52:55]
	v_mfma_f32_16x16x32_bf16 v[48:51], v[156:159], v[196:199], v[48:51]
	v_mfma_f32_16x16x32_bf16 v[36:39], v[148:151], v[204:207], v[36:39]
	v_mfma_f32_16x16x32_bf16 v[32:35], v[156:159], v[204:207], v[32:35]
	v_mfma_f32_16x16x32_bf16 v[20:23], v[148:151], v[212:215], v[20:23]
	v_mfma_f32_16x16x32_bf16 v[16:19], v[156:159], v[212:215], v[16:19]
	v_mfma_f32_16x16x32_bf16 v[4:7], v[148:151], v[220:223], v[4:7]
	v_mfma_f32_16x16x32_bf16 v[0:3], v[156:159], v[220:223], v[0:3]
	s_setprio 0
	s_barrier
	s_add_i32 s52, s52, 2
	s_add_u32 s0, s0, 0x100
	s_addc_u32 s1, s1, 0
	s_add_u32 s50, s50, 0x100
	s_addc_u32 s51, s51, 0
	s_cmp_gt_u32 s52, 61
	s_cbranch_scc0 .LBB0_1563
	s_branch .Lpeel_exit_8
